# GEMM loops: fragment reads of each section hoisted ahead of the staged global-load issue (right after the LDS-write barrier)
# baseline (speedup 1.0000x reference)
; DEV f32x4 mfma16(bf16x8 a, bf16x8 b, f32x4 c) { return __builtin_amdgcn_mfma_f32_16x16x32_bf16(a, b, c, 0, 0, 0); }
; #define G_LOAD(RA, RB, KT) { _Pragma("unroll") for (int i = 0; i < 4; i++) { \
;       RA[i] = *(const u32x4*)(Ap + (size_t)(i * 32) * lda + (KT) * 64); RB[i] = *(const u32x4*)(Bp + (size_t)(i * 32) * ldb + (KT) * 64); } }
; #define G_STORE(RA, RB) { _Pragma("unroll") for (int i = 0; i < 4; i++) { \
;       *(u32x4*)(As + (lrow + i * 32) * GLD + lcc * 8) = RA[i]; *(u32x4*)(Bs + (lrow + i * 32) * GLD + lcc * 8) = RB[i]; } }
; template <int TI, int TJ, int KS>
; DEV void mfma_lds(const bf16_t* Arows, int lda, const bf16_t* Brows, int ldb, int i0, int j0, f32x4 (&acc)[TI][TJ]) {
;     ...
;   for (int ks = 0; ks < KS; ks++) {
;     bf16x8 af[TI], bfr[TJ];
; #pragma unroll
;     for (int i = 0; i < TI; i++) af[i] = *(const bf16x8*)(Arows + (i0 + i * 16 + l15) * lda + ks * 32 + quad * 8);
; #pragma unroll
;     for (int j = 0; j < TJ; j++) bfr[j] = *(const bf16x8*)(Brows + (j0 + j * 16 + l15) * ldb + ks * 32 + quad * 8);
; #pragma unroll
;     for (int i = 0; i < TI; i++)
; #pragma unroll
;       for (int j = 0; j < TJ; j++) acc[i][j] = mfma16(af[i], bfr[j], acc[i][j]);
;   }
; template <class Epi>
; DEV void gemm_tile(const bf16_t* __restrict__ A, int lda, const bf16_t* __restrict__ Bt, int ldb, int K, int m0, int n0,
;                    Epi& epi, char* smem) {
;     ...
;   for (int kt = 0; kt < nk; kt += 2) {
;     __syncthreads();
;     G_STORE(ra0, rb0);
;     __syncthreads();
;     if (kt + 2 < nk) G_LOAD(ra0, rb0, kt + 2);
;     mfma_lds<4, 4, 2>(Bs, GLD, As, GLD, wn * 64, wm * 64, acc);
;     __syncthreads();
;     G_STORE(ra1, rb1);
;     __syncthreads();
;     if (kt + 3 < nk) G_LOAD(ra1, rb1, kt + 3);
;     mfma_lds<4, 4, 2>(Bs, GLD, As, GLD, wn * 64, wm * 64, acc);
;   }
.LBB0_181:
	v_lshl_add_u64 v[136:137], v[136:137], 0, s[34:35]
	v_lshl_add_u64 v[138:139], v[138:139], 0, s[34:35]
	s_andn2_b64 vcc, exec, s[14:15]
	s_waitcnt lgkmcnt(8)
	v_mfma_f32_16x16x32_bf16 v[106:109], v[148:151], v[164:167], v[106:109]
	s_waitcnt lgkmcnt(7)
	v_mfma_f32_16x16x32_bf16 v[122:125], v[148:151], v[168:171], v[122:125]
	s_waitcnt lgkmcnt(6)
	v_mfma_f32_16x16x32_bf16 v[114:117], v[148:151], v[172:175], v[114:117]
	s_waitcnt lgkmcnt(5)
	v_mfma_f32_16x16x32_bf16 v[110:113], v[148:151], v[176:179], v[110:113]
	ds_read_b128 v[148:151], v147 offset:20544
	s_waitcnt lgkmcnt(5)
	v_mfma_f32_16x16x32_bf16 v[102:105], v[152:155], v[164:167], v[102:105]
	v_mfma_f32_16x16x32_bf16 v[94:97], v[152:155], v[168:171], v[94:97]
	v_mfma_f32_16x16x32_bf16 v[86:89], v[152:155], v[172:175], v[86:89]
	v_mfma_f32_16x16x32_bf16 v[78:81], v[152:155], v[176:179], v[78:81]
	ds_read_b128 v[152:155], v147 offset:23104
	s_waitcnt lgkmcnt(5)
	v_mfma_f32_16x16x32_bf16 v[82:85], v[156:159], v[164:167], v[82:85]
	v_mfma_f32_16x16x32_bf16 v[74:77], v[156:159], v[168:171], v[74:77]
	v_mfma_f32_16x16x32_bf16 v[70:73], v[156:159], v[172:175], v[70:73]
	v_mfma_f32_16x16x32_bf16 v[66:69], v[156:159], v[176:179], v[66:69]
	ds_read_b128 v[156:159], v147 offset:25664
	s_waitcnt lgkmcnt(5)
	v_mfma_f32_16x16x32_bf16 v[126:129], v[160:163], v[172:175], v[126:129]
	v_mfma_f32_16x16x32_bf16 v[118:121], v[160:163], v[176:179], v[118:121]
	ds_read_b128 v[172:175], v238 offset:5184
	ds_read_b128 v[176:179], v238 offset:7744
	v_mfma_f32_16x16x32_bf16 v[98:101], v[160:163], v[164:167], v[98:101]
	v_mfma_f32_16x16x32_bf16 v[90:93], v[160:163], v[168:171], v[90:93]
	ds_read_b128 v[160:163], v147 offset:28224
	s_waitcnt lgkmcnt(5)
	v_mfma_f32_16x16x32_bf16 v[106:109], v[148:151], v[180:183], v[106:109]
	s_waitcnt lgkmcnt(4)
	v_mfma_f32_16x16x32_bf16 v[102:105], v[152:155], v[180:183], v[102:105]
	s_waitcnt lgkmcnt(3)
	v_mfma_f32_16x16x32_bf16 v[82:85], v[156:159], v[180:183], v[82:85]
	v_mfma_f32_16x16x32_bf16 v[122:125], v[148:151], v[184:187], v[122:125]
	v_mfma_f32_16x16x32_bf16 v[94:97], v[152:155], v[184:187], v[94:97]
	v_mfma_f32_16x16x32_bf16 v[74:77], v[156:159], v[184:187], v[74:77]
	s_waitcnt lgkmcnt(2)
	v_mfma_f32_16x16x32_bf16 v[114:117], v[148:151], v[172:175], v[114:117]
	v_mfma_f32_16x16x32_bf16 v[86:89], v[152:155], v[172:175], v[86:89]
	v_mfma_f32_16x16x32_bf16 v[70:73], v[156:159], v[172:175], v[70:73]
	s_waitcnt lgkmcnt(1)
	v_mfma_f32_16x16x32_bf16 v[110:113], v[148:151], v[176:179], v[110:113]
	v_mfma_f32_16x16x32_bf16 v[78:81], v[152:155], v[176:179], v[78:81]
	v_mfma_f32_16x16x32_bf16 v[66:69], v[156:159], v[176:179], v[66:69]
	s_waitcnt lgkmcnt(0)
	v_mfma_f32_16x16x32_bf16 v[98:101], v[160:163], v[180:183], v[98:101]
	v_mfma_f32_16x16x32_bf16 v[90:93], v[160:163], v[184:187], v[90:93]
	v_mfma_f32_16x16x32_bf16 v[126:129], v[160:163], v[172:175], v[126:129]
	v_mfma_f32_16x16x32_bf16 v[118:121], v[160:163], v[176:179], v[118:121]
	s_cbranch_vccz .LBB0_177
.LBB0_182:
	s_add_i32 s12, s12, 2
	s_cmp_gt_u32 s12, 13
	s_cselect_b64 s[14:15], -1, 0
	s_and_b64 vcc, exec, s[14:15]
	v_lshl_add_u64 v[142:143], v[138:139], 0, v[0:1]
	v_lshl_add_u64 v[140:141], v[136:137], 0, v[0:1]
	s_waitcnt lgkmcnt(0)
	s_barrier
	s_waitcnt vmcnt(8)
	ds_write_b128 v134, v[2:5]
	ds_write_b128 v134, v[10:13] offset:20480
	ds_write_b128 v134, v[18:21] offset:5120
	ds_write_b128 v134, v[26:29] offset:25600
	ds_write_b128 v134, v[34:37] offset:10240
	ds_write_b128 v134, v[42:45] offset:30720
	ds_write_b128 v134, v[50:53] offset:15360
	ds_write_b128 v134, v[58:61] offset:35840
	s_waitcnt lgkmcnt(0)
	s_barrier
	v_mov_b32_e32 v130, v195
	v_and_b32_e32 v135, 15, v130
	v_or_b32_e32 v131, v135, v144
	v_and_b32_e32 v148, 48, v130
	v_mul_u32_u24_e32 v130, 0x50, v131
	v_lshl_add_u32 v147, v130, 1, v148
	v_or_b32_e32 v135, v135, v146
	v_mad_u32_u24 v238, v135, s36, v148
	ds_read_b128 v[148:151], v147 offset:20480
	ds_read_b128 v[164:167], v238
	ds_read_b128 v[168:171], v238 offset:2560
	ds_read_b128 v[172:175], v238 offset:5120
	ds_read_b128 v[176:179], v238 offset:7680
	ds_read_b128 v[152:155], v147 offset:23040
	ds_read_b128 v[156:159], v147 offset:25600
	ds_read_b128 v[160:163], v147 offset:28160
	ds_read_b128 v[180:183], v238 offset:64
	ds_read_b128 v[184:187], v238 offset:2624
	s_cbranch_vccnz .Lgw_skip_0
	v_add_co_u32_e32 v2, vcc, 0x4200000, v142
	s_nop 1
	v_addc_co_u32_e32 v3, vcc, 0, v143, vcc
	v_add_co_u32_e32 v10, vcc, 0xba00000, v140
	global_load_dwordx4 v[2:5], v[2:3], off offset:256
	s_nop 0
	v_addc_co_u32_e32 v11, vcc, 0, v141, vcc
	v_add_co_u32_e32 v18, vcc, 0x4211000, v142
	global_load_dwordx4 v[10:13], v[10:11], off offset:256
	s_nop 0
	v_addc_co_u32_e32 v19, vcc, 0, v143, vcc
	v_add_co_u32_e32 v26, vcc, 0xba11000, v140
	global_load_dwordx4 v[18:21], v[18:19], off offset:256
	s_nop 0
	v_addc_co_u32_e32 v27, vcc, 0, v141, vcc
	v_add_co_u32_e32 v34, vcc, 0x4222000, v142
	global_load_dwordx4 v[26:29], v[26:27], off offset:256
	s_nop 0
	v_addc_co_u32_e32 v35, vcc, 0, v143, vcc
	v_add_co_u32_e32 v42, vcc, 0xba22000, v140
	global_load_dwordx4 v[34:37], v[34:35], off offset:256
	s_nop 0
	v_addc_co_u32_e32 v43, vcc, 0, v141, vcc
	v_add_co_u32_e32 v50, vcc, 0x4233000, v142
	global_load_dwordx4 v[42:45], v[42:43], off offset:256
	s_nop 0
	v_addc_co_u32_e32 v51, vcc, 0, v143, vcc
	v_add_co_u32_e32 v58, vcc, 0xba33000, v140
	global_load_dwordx4 v[50:53], v[50:51], off offset:256
	s_nop 0
	v_addc_co_u32_e32 v59, vcc, 0, v141, vcc
	global_load_dwordx4 v[58:61], v[58:59], off offset:256
; DEV f32x4 mfma16(bf16x8 a, bf16x8 b, f32x4 c) { return __builtin_amdgcn_mfma_f32_16x16x32_bf16(a, b, c, 0, 0, 0); }
; #define G_LOAD(RA, RB, KT) { _Pragma("unroll") for (int i = 0; i < 4; i++) { \
;       RA[i] = *(const u32x4*)(Ap + (size_t)(i * 32) * lda + (KT) * 64); RB[i] = *(const u32x4*)(Bp + (size_t)(i * 32) * ldb + (KT) * 64); } }
; #define G_STORE(RA, RB) { _Pragma("unroll") for (int i = 0; i < 4; i++) { \
;       *(u32x4*)(As + (lrow + i * 32) * GLD + lcc * 8) = RA[i]; *(u32x4*)(Bs + (lrow + i * 32) * GLD + lcc * 8) = RB[i]; } }
; template <int TI, int TJ, int KS>
; DEV void mfma_lds(const bf16_t* Arows, int lda, const bf16_t* Brows, int ldb, int i0, int j0, f32x4 (&acc)[TI][TJ]) {
;     ...
;   for (int ks = 0; ks < KS; ks++) {
;     bf16x8 af[TI], bfr[TJ];
; #pragma unroll
;     for (int i = 0; i < TI; i++) af[i] = *(const bf16x8*)(Arows + (i0 + i * 16 + l15) * lda + ks * 32 + quad * 8);
; #pragma unroll
;     for (int j = 0; j < TJ; j++) bfr[j] = *(const bf16x8*)(Brows + (j0 + j * 16 + l15) * ldb + ks * 32 + quad * 8);
; #pragma unroll
;     for (int i = 0; i < TI; i++)
; #pragma unroll
;       for (int j = 0; j < TJ; j++) acc[i][j] = mfma16(af[i], bfr[j], acc[i][j]);
;   }
; template <class Epi>
; DEV void gemm_tile(const bf16_t* __restrict__ A, int lda, const bf16_t* __restrict__ Bt, int ldb, int K, int m0, int n0,
;                    Epi& epi, char* smem) {
;     ...
;   for (int kt = 0; kt < nk; kt += 2) {
;     __syncthreads();
;     G_STORE(ra0, rb0);
;     __syncthreads();
;     if (kt + 2 < nk) G_LOAD(ra0, rb0, kt + 2);
;     mfma_lds<4, 4, 2>(Bs, GLD, As, GLD, wn * 64, wm * 64, acc);
;     __syncthreads();
;     G_STORE(ra1, rb1);
;     __syncthreads();
;     if (kt + 3 < nk) G_LOAD(ra1, rb1, kt + 3);
;     mfma_lds<4, 4, 2>(Bs, GLD, As, GLD, wn * 64, wm * 64, acc);
;   }
.LBB0_184:
	s_cmp_gt_u32 s12, 12
	s_waitcnt lgkmcnt(8)
	v_mfma_f32_16x16x32_bf16 v[106:109], v[148:151], v[164:167], v[106:109]
	s_waitcnt lgkmcnt(7)
	v_mfma_f32_16x16x32_bf16 v[122:125], v[148:151], v[168:171], v[122:125]
	s_waitcnt lgkmcnt(6)
	v_mfma_f32_16x16x32_bf16 v[114:117], v[148:151], v[172:175], v[114:117]
	s_waitcnt lgkmcnt(5)
	v_mfma_f32_16x16x32_bf16 v[110:113], v[148:151], v[176:179], v[110:113]
	ds_read_b128 v[148:151], v147 offset:20544
	s_waitcnt lgkmcnt(5)
	v_mfma_f32_16x16x32_bf16 v[102:105], v[152:155], v[164:167], v[102:105]
	v_mfma_f32_16x16x32_bf16 v[94:97], v[152:155], v[168:171], v[94:97]
	v_mfma_f32_16x16x32_bf16 v[86:89], v[152:155], v[172:175], v[86:89]
	v_mfma_f32_16x16x32_bf16 v[78:81], v[152:155], v[176:179], v[78:81]
	ds_read_b128 v[152:155], v147 offset:23104
	s_waitcnt lgkmcnt(5)
	v_mfma_f32_16x16x32_bf16 v[82:85], v[156:159], v[164:167], v[82:85]
	v_mfma_f32_16x16x32_bf16 v[74:77], v[156:159], v[168:171], v[74:77]
	v_mfma_f32_16x16x32_bf16 v[70:73], v[156:159], v[172:175], v[70:73]
	v_mfma_f32_16x16x32_bf16 v[66:69], v[156:159], v[176:179], v[66:69]
	ds_read_b128 v[156:159], v147 offset:25664
	s_waitcnt lgkmcnt(5)
	v_mfma_f32_16x16x32_bf16 v[126:129], v[160:163], v[172:175], v[126:129]
	v_mfma_f32_16x16x32_bf16 v[118:121], v[160:163], v[176:179], v[118:121]
	ds_read_b128 v[172:175], v238 offset:5184
	ds_read_b128 v[176:179], v238 offset:7744
	v_mfma_f32_16x16x32_bf16 v[98:101], v[160:163], v[164:167], v[98:101]
	v_mfma_f32_16x16x32_bf16 v[90:93], v[160:163], v[168:171], v[90:93]
	ds_read_b128 v[160:163], v147 offset:28224
	s_waitcnt lgkmcnt(5)
	v_mfma_f32_16x16x32_bf16 v[106:109], v[148:151], v[180:183], v[106:109]
	s_waitcnt lgkmcnt(4)
	v_mfma_f32_16x16x32_bf16 v[102:105], v[152:155], v[180:183], v[102:105]
	s_waitcnt lgkmcnt(3)
	v_mfma_f32_16x16x32_bf16 v[82:85], v[156:159], v[180:183], v[82:85]
	v_mfma_f32_16x16x32_bf16 v[122:125], v[148:151], v[184:187], v[122:125]
	v_mfma_f32_16x16x32_bf16 v[94:97], v[152:155], v[184:187], v[94:97]
	v_mfma_f32_16x16x32_bf16 v[74:77], v[156:159], v[184:187], v[74:77]
	s_waitcnt lgkmcnt(2)
	v_mfma_f32_16x16x32_bf16 v[114:117], v[148:151], v[172:175], v[114:117]
	v_mfma_f32_16x16x32_bf16 v[86:89], v[152:155], v[172:175], v[86:89]
	v_mfma_f32_16x16x32_bf16 v[70:73], v[156:159], v[172:175], v[70:73]
	s_waitcnt lgkmcnt(1)
	v_mfma_f32_16x16x32_bf16 v[110:113], v[148:151], v[176:179], v[110:113]
	v_mfma_f32_16x16x32_bf16 v[78:81], v[152:155], v[176:179], v[78:81]
	v_mfma_f32_16x16x32_bf16 v[66:69], v[156:159], v[176:179], v[66:69]
	s_waitcnt lgkmcnt(0)
	v_mfma_f32_16x16x32_bf16 v[98:101], v[160:163], v[180:183], v[98:101]
	s_barrier
	v_mfma_f32_16x16x32_bf16 v[90:93], v[160:163], v[184:187], v[90:93]
	s_waitcnt vmcnt(8)
	ds_write_b128 v134, v[6:9]
	ds_write_b128 v134, v[14:17] offset:20480
	ds_write_b128 v134, v[22:25] offset:5120
	ds_write_b128 v134, v[30:33] offset:25600
	ds_write_b128 v134, v[38:41] offset:10240
	ds_write_b128 v134, v[46:49] offset:30720
	ds_write_b128 v134, v[54:57] offset:15360
	ds_write_b128 v134, v[62:65] offset:35840
	v_mfma_f32_16x16x32_bf16 v[126:129], v[160:163], v[172:175], v[126:129]
	v_mfma_f32_16x16x32_bf16 v[118:121], v[160:163], v[176:179], v[118:121]
	s_waitcnt lgkmcnt(0)
	s_barrier
	ds_read_b128 v[148:151], v147 offset:20480
	ds_read_b128 v[164:167], v238
	ds_read_b128 v[168:171], v238 offset:2560
	ds_read_b128 v[172:175], v238 offset:5120
	ds_read_b128 v[176:179], v238 offset:7680
	ds_read_b128 v[152:155], v147 offset:23040
	ds_read_b128 v[156:159], v147 offset:25600
	ds_read_b128 v[160:163], v147 offset:28160
	ds_read_b128 v[180:183], v238 offset:64
	ds_read_b128 v[184:187], v238 offset:2624
	s_cbranch_scc1 .LBB0_181
	v_add_co_u32_e32 v6, vcc, 0x4200000, v142
	s_nop 1
	v_addc_co_u32_e32 v7, vcc, 0, v143, vcc
	v_add_co_u32_e32 v14, vcc, 0xba00000, v140
	global_load_dwordx4 v[6:9], v[6:7], off offset:384
	s_nop 0
	v_addc_co_u32_e32 v15, vcc, 0, v141, vcc
	v_add_co_u32_e32 v22, vcc, 0x4211000, v142
	global_load_dwordx4 v[14:17], v[14:15], off offset:384
	s_nop 0
	v_addc_co_u32_e32 v23, vcc, 0, v143, vcc
	v_add_co_u32_e32 v30, vcc, 0xba11000, v140
	global_load_dwordx4 v[22:25], v[22:23], off offset:384
	s_nop 0
	v_addc_co_u32_e32 v31, vcc, 0, v141, vcc
	v_add_co_u32_e32 v38, vcc, 0x4222000, v142
	global_load_dwordx4 v[30:33], v[30:31], off offset:384
	s_nop 0
	v_addc_co_u32_e32 v39, vcc, 0, v143, vcc
	v_add_co_u32_e32 v46, vcc, 0xba22000, v140
	global_load_dwordx4 v[38:41], v[38:39], off offset:384
	s_nop 0
	v_addc_co_u32_e32 v47, vcc, 0, v141, vcc
	v_add_co_u32_e32 v54, vcc, 0x4233000, v142
	global_load_dwordx4 v[46:49], v[46:47], off offset:384
	s_nop 0
	v_addc_co_u32_e32 v55, vcc, 0, v143, vcc
	v_add_co_u32_e32 v62, vcc, 0xba33000, v140
	global_load_dwordx4 v[54:57], v[54:55], off offset:384
	s_nop 0
	v_addc_co_u32_e32 v63, vcc, 0, v141, vcc
	global_load_dwordx4 v[62:65], v[62:63], off offset:384
	s_branch .LBB0_181

; DEV f32x4 mfma16(bf16x8 a, bf16x8 b, f32x4 c) { return __builtin_amdgcn_mfma_f32_16x16x32_bf16(a, b, c, 0, 0, 0); }
; #define G_LOAD(RA, RB, KT) { _Pragma("unroll") for (int i = 0; i < 4; i++) { \
;       RA[i] = *(const u32x4*)(Ap + (size_t)(i * 32) * lda + (KT) * 64); RB[i] = *(const u32x4*)(Bp + (size_t)(i * 32) * ldb + (KT) * 64); } }
; #define G_STORE(RA, RB) { _Pragma("unroll") for (int i = 0; i < 4; i++) { \
;       *(u32x4*)(As + (lrow + i * 32) * GLD + lcc * 8) = RA[i]; *(u32x4*)(Bs + (lrow + i * 32) * GLD + lcc * 8) = RB[i]; } }
; template <int TI, int TJ, int KS>
; DEV void mfma_lds(const bf16_t* Arows, int lda, const bf16_t* Brows, int ldb, int i0, int j0, f32x4 (&acc)[TI][TJ]) {
;     ...
;   for (int ks = 0; ks < KS; ks++) {
;     bf16x8 af[TI], bfr[TJ];
; #pragma unroll
;     for (int i = 0; i < TI; i++) af[i] = *(const bf16x8*)(Arows + (i0 + i * 16 + l15) * lda + ks * 32 + quad * 8);
; #pragma unroll
;     for (int j = 0; j < TJ; j++) bfr[j] = *(const bf16x8*)(Brows + (j0 + j * 16 + l15) * ldb + ks * 32 + quad * 8);
; #pragma unroll
;     for (int i = 0; i < TI; i++)
; #pragma unroll
;       for (int j = 0; j < TJ; j++) acc[i][j] = mfma16(af[i], bfr[j], acc[i][j]);
;   }
; template <class Epi>
; DEV void gemm_tile(const bf16_t* __restrict__ A, int lda, const bf16_t* __restrict__ Bt, int ldb, int K, int m0, int n0,
;                    Epi& epi, char* smem) {
;     ...
;   for (int kt = 0; kt < nk; kt += 2) {
;     __syncthreads();
;     G_STORE(ra0, rb0);
;     __syncthreads();
;     if (kt + 2 < nk) G_LOAD(ra0, rb0, kt + 2);
;     mfma_lds<4, 4, 2>(Bs, GLD, As, GLD, wn * 64, wm * 64, acc);
;     __syncthreads();
;     G_STORE(ra1, rb1);
;     __syncthreads();
;     if (kt + 3 < nk) G_LOAD(ra1, rb1, kt + 3);
;     mfma_lds<4, 4, 2>(Bs, GLD, As, GLD, wn * 64, wm * 64, acc);
;   }
.LBB0_200:
	v_lshl_add_u64 v[132:133], v[132:133], 0, s[34:35]
	v_lshl_add_u64 v[134:135], v[134:135], 0, s[34:35]
	s_and_b64 vcc, exec, s[16:17]
	s_waitcnt lgkmcnt(8)
	v_mfma_f32_16x16x32_bf16 v[126:129], v[144:147], v[160:163], v[126:129]
	s_waitcnt lgkmcnt(7)
	v_mfma_f32_16x16x32_bf16 v[122:125], v[144:147], v[164:167], v[122:125]
	s_waitcnt lgkmcnt(6)
	v_mfma_f32_16x16x32_bf16 v[118:121], v[144:147], v[168:171], v[118:121]
	s_waitcnt lgkmcnt(5)
	v_mfma_f32_16x16x32_bf16 v[114:117], v[144:147], v[172:175], v[114:117]
	ds_read_b128 v[144:147], v131 offset:20544
	s_waitcnt lgkmcnt(5)
	v_mfma_f32_16x16x32_bf16 v[110:113], v[148:151], v[160:163], v[110:113]
	v_mfma_f32_16x16x32_bf16 v[74:77], v[148:151], v[164:167], v[74:77]
	v_mfma_f32_16x16x32_bf16 v[38:41], v[148:151], v[168:171], v[38:41]
	v_mfma_f32_16x16x32_bf16 v[34:37], v[148:151], v[172:175], v[34:37]
	ds_read_b128 v[148:151], v131 offset:23104
	s_waitcnt lgkmcnt(5)
	v_mfma_f32_16x16x32_bf16 v[30:33], v[152:155], v[160:163], v[30:33]
	v_mfma_f32_16x16x32_bf16 v[26:29], v[152:155], v[164:167], v[26:29]
	v_mfma_f32_16x16x32_bf16 v[22:25], v[152:155], v[168:171], v[22:25]
	v_mfma_f32_16x16x32_bf16 v[18:21], v[152:155], v[172:175], v[18:21]
	ds_read_b128 v[152:155], v131 offset:25664
	s_waitcnt lgkmcnt(5)
	v_mfma_f32_16x16x32_bf16 v[6:9], v[156:159], v[168:171], v[6:9]
	v_mfma_f32_16x16x32_bf16 v[2:5], v[156:159], v[172:175], v[2:5]
	ds_read_b128 v[168:171], v238 offset:5184
	ds_read_b128 v[172:175], v238 offset:7744
	v_mfma_f32_16x16x32_bf16 v[14:17], v[156:159], v[160:163], v[14:17]
	v_mfma_f32_16x16x32_bf16 v[10:13], v[156:159], v[164:167], v[10:13]
	ds_read_b128 v[156:159], v131 offset:28224
	s_waitcnt lgkmcnt(5)
	v_mfma_f32_16x16x32_bf16 v[126:129], v[144:147], v[176:179], v[126:129]
	s_waitcnt lgkmcnt(4)
	v_mfma_f32_16x16x32_bf16 v[110:113], v[148:151], v[176:179], v[110:113]
	s_waitcnt lgkmcnt(3)
	v_mfma_f32_16x16x32_bf16 v[30:33], v[152:155], v[176:179], v[30:33]
	v_mfma_f32_16x16x32_bf16 v[122:125], v[144:147], v[180:183], v[122:125]
	v_mfma_f32_16x16x32_bf16 v[74:77], v[148:151], v[180:183], v[74:77]
	v_mfma_f32_16x16x32_bf16 v[26:29], v[152:155], v[180:183], v[26:29]
	s_waitcnt lgkmcnt(2)
	v_mfma_f32_16x16x32_bf16 v[118:121], v[144:147], v[168:171], v[118:121]
	v_mfma_f32_16x16x32_bf16 v[38:41], v[148:151], v[168:171], v[38:41]
	v_mfma_f32_16x16x32_bf16 v[22:25], v[152:155], v[168:171], v[22:25]
	s_waitcnt lgkmcnt(1)
	v_mfma_f32_16x16x32_bf16 v[114:117], v[144:147], v[172:175], v[114:117]
	v_mfma_f32_16x16x32_bf16 v[34:37], v[148:151], v[172:175], v[34:37]
	v_mfma_f32_16x16x32_bf16 v[18:21], v[152:155], v[172:175], v[18:21]
	s_waitcnt lgkmcnt(0)
	v_mfma_f32_16x16x32_bf16 v[14:17], v[156:159], v[176:179], v[14:17]
	v_mfma_f32_16x16x32_bf16 v[10:13], v[156:159], v[180:183], v[10:13]
	v_mfma_f32_16x16x32_bf16 v[6:9], v[156:159], v[168:171], v[6:9]
	v_mfma_f32_16x16x32_bf16 v[2:5], v[156:159], v[172:175], v[2:5]
	s_cbranch_vccnz .LBB0_205
.LBB0_201:
	s_add_i32 s1, s1, 2
	s_cmp_gt_u32 s1, 13
	s_cselect_b64 s[16:17], -1, 0
	s_and_b64 vcc, exec, s[16:17]
	v_lshl_add_u64 v[138:139], v[134:135], 0, v[0:1]
	v_lshl_add_u64 v[136:137], v[132:133], 0, v[0:1]
	s_waitcnt lgkmcnt(0)
	s_barrier
	s_waitcnt vmcnt(8)
	ds_write_b128 v130, v[42:45]
	ds_write_b128 v130, v[50:53] offset:20480
	ds_write_b128 v130, v[58:61] offset:5120
	ds_write_b128 v130, v[66:69] offset:25600
	ds_write_b128 v130, v[78:81] offset:10240
	ds_write_b128 v130, v[86:89] offset:30720
	ds_write_b128 v130, v[94:97] offset:15360
	ds_write_b128 v130, v[102:105] offset:35840
	s_waitcnt lgkmcnt(0)
	s_barrier
	v_mov_b32_e32 v131, v195
	v_and_b32_e32 v143, 15, v131
	v_or_b32_e32 v144, v143, v140
	v_and_b32_e32 v148, 48, v131
	v_mul_u32_u24_e32 v131, 0x50, v144
	v_lshl_add_u32 v131, v131, 1, v148
	v_or_b32_e32 v143, v143, v142
	v_mad_u32_u24 v238, v143, s36, v148
	ds_read_b128 v[144:147], v131 offset:20480
	ds_read_b128 v[160:163], v238
	ds_read_b128 v[164:167], v238 offset:2560
	ds_read_b128 v[168:171], v238 offset:5120
	ds_read_b128 v[172:175], v238 offset:7680
	ds_read_b128 v[148:151], v131 offset:23040
	ds_read_b128 v[152:155], v131 offset:25600
	ds_read_b128 v[156:159], v131 offset:28160
	ds_read_b128 v[176:179], v238 offset:64
	ds_read_b128 v[180:183], v238 offset:2624
	s_cbranch_vccnz .Lgw_skip_1
	v_add_co_u32_e32 v42, vcc, 0x4200000, v138
	s_nop 1
	v_addc_co_u32_e32 v43, vcc, 0, v139, vcc
	v_add_co_u32_e32 v50, vcc, 0xb3a0000, v136
	global_load_dwordx4 v[42:45], v[42:43], off offset:256
	s_nop 0
	v_addc_co_u32_e32 v51, vcc, 0, v137, vcc
	v_add_co_u32_e32 v58, vcc, 0x4211000, v138
	global_load_dwordx4 v[50:53], v[50:51], off offset:256
	s_nop 0
	v_addc_co_u32_e32 v59, vcc, 0, v139, vcc
	v_add_co_u32_e32 v66, vcc, 0xb3b1000, v136
	global_load_dwordx4 v[58:61], v[58:59], off offset:256
	s_nop 0
	v_addc_co_u32_e32 v67, vcc, 0, v137, vcc
	v_add_co_u32_e32 v78, vcc, 0x4222000, v138
	global_load_dwordx4 v[66:69], v[66:67], off offset:256
	s_nop 0
	v_addc_co_u32_e32 v79, vcc, 0, v139, vcc
	v_add_co_u32_e32 v86, vcc, 0xb3c2000, v136
	global_load_dwordx4 v[78:81], v[78:79], off offset:256
	s_nop 0
	v_addc_co_u32_e32 v87, vcc, 0, v137, vcc
	v_add_co_u32_e32 v94, vcc, 0x4233000, v138
	global_load_dwordx4 v[86:89], v[86:87], off offset:256
	s_nop 0
	v_addc_co_u32_e32 v95, vcc, 0, v139, vcc
	v_add_co_u32_e32 v102, vcc, 0xb3d3000, v136
	global_load_dwordx4 v[94:97], v[94:95], off offset:256
	s_nop 0
	v_addc_co_u32_e32 v103, vcc, 0, v137, vcc
	global_load_dwordx4 v[102:105], v[102:103], off offset:256
; DEV f32x4 mfma16(bf16x8 a, bf16x8 b, f32x4 c) { return __builtin_amdgcn_mfma_f32_16x16x32_bf16(a, b, c, 0, 0, 0); }
; #define G_LOAD(RA, RB, KT) { _Pragma("unroll") for (int i = 0; i < 4; i++) { \
;       RA[i] = *(const u32x4*)(Ap + (size_t)(i * 32) * lda + (KT) * 64); RB[i] = *(const u32x4*)(Bp + (size_t)(i * 32) * ldb + (KT) * 64); } }
; #define G_STORE(RA, RB) { _Pragma("unroll") for (int i = 0; i < 4; i++) { \
;       *(u32x4*)(As + (lrow + i * 32) * GLD + lcc * 8) = RA[i]; *(u32x4*)(Bs + (lrow + i * 32) * GLD + lcc * 8) = RB[i]; } }
; template <int TI, int TJ, int KS>
; DEV void mfma_lds(const bf16_t* Arows, int lda, const bf16_t* Brows, int ldb, int i0, int j0, f32x4 (&acc)[TI][TJ]) {
;     ...
;   for (int ks = 0; ks < KS; ks++) {
;     bf16x8 af[TI], bfr[TJ];
; #pragma unroll
;     for (int i = 0; i < TI; i++) af[i] = *(const bf16x8*)(Arows + (i0 + i * 16 + l15) * lda + ks * 32 + quad * 8);
; #pragma unroll
;     for (int j = 0; j < TJ; j++) bfr[j] = *(const bf16x8*)(Brows + (j0 + j * 16 + l15) * ldb + ks * 32 + quad * 8);
; #pragma unroll
;     for (int i = 0; i < TI; i++)
; #pragma unroll
;       for (int j = 0; j < TJ; j++) acc[i][j] = mfma16(af[i], bfr[j], acc[i][j]);
;   }
; template <class Epi>
; DEV void gemm_tile(const bf16_t* __restrict__ A, int lda, const bf16_t* __restrict__ Bt, int ldb, int K, int m0, int n0,
;                    Epi& epi, char* smem) {
;     ...
;   for (int kt = 0; kt < nk; kt += 2) {
;     __syncthreads();
;     G_STORE(ra0, rb0);
;     __syncthreads();
;     if (kt + 2 < nk) G_LOAD(ra0, rb0, kt + 2);
;     mfma_lds<4, 4, 2>(Bs, GLD, As, GLD, wn * 64, wm * 64, acc);
;     __syncthreads();
;     G_STORE(ra1, rb1);
;     __syncthreads();
;     if (kt + 3 < nk) G_LOAD(ra1, rb1, kt + 3);
;     mfma_lds<4, 4, 2>(Bs, GLD, As, GLD, wn * 64, wm * 64, acc);
;   }
.LBB0_203:
	s_cmp_gt_u32 s1, 12
	s_waitcnt lgkmcnt(8)
	v_mfma_f32_16x16x32_bf16 v[126:129], v[144:147], v[160:163], v[126:129]
	s_waitcnt lgkmcnt(7)
	v_mfma_f32_16x16x32_bf16 v[122:125], v[144:147], v[164:167], v[122:125]
	s_waitcnt lgkmcnt(6)
	v_mfma_f32_16x16x32_bf16 v[118:121], v[144:147], v[168:171], v[118:121]
	s_waitcnt lgkmcnt(5)
	v_mfma_f32_16x16x32_bf16 v[114:117], v[144:147], v[172:175], v[114:117]
	ds_read_b128 v[144:147], v131 offset:20544
	s_waitcnt lgkmcnt(5)
	v_mfma_f32_16x16x32_bf16 v[110:113], v[148:151], v[160:163], v[110:113]
	v_mfma_f32_16x16x32_bf16 v[74:77], v[148:151], v[164:167], v[74:77]
	v_mfma_f32_16x16x32_bf16 v[38:41], v[148:151], v[168:171], v[38:41]
	v_mfma_f32_16x16x32_bf16 v[34:37], v[148:151], v[172:175], v[34:37]
	ds_read_b128 v[148:151], v131 offset:23104
	s_waitcnt lgkmcnt(5)
	v_mfma_f32_16x16x32_bf16 v[30:33], v[152:155], v[160:163], v[30:33]
	v_mfma_f32_16x16x32_bf16 v[26:29], v[152:155], v[164:167], v[26:29]
	v_mfma_f32_16x16x32_bf16 v[22:25], v[152:155], v[168:171], v[22:25]
	v_mfma_f32_16x16x32_bf16 v[18:21], v[152:155], v[172:175], v[18:21]
	ds_read_b128 v[152:155], v131 offset:25664
	s_waitcnt lgkmcnt(5)
	v_mfma_f32_16x16x32_bf16 v[6:9], v[156:159], v[168:171], v[6:9]
	v_mfma_f32_16x16x32_bf16 v[2:5], v[156:159], v[172:175], v[2:5]
	ds_read_b128 v[168:171], v238 offset:5184
	ds_read_b128 v[172:175], v238 offset:7744
	v_mfma_f32_16x16x32_bf16 v[14:17], v[156:159], v[160:163], v[14:17]
	v_mfma_f32_16x16x32_bf16 v[10:13], v[156:159], v[164:167], v[10:13]
	ds_read_b128 v[156:159], v131 offset:28224
	s_waitcnt lgkmcnt(5)
	v_mfma_f32_16x16x32_bf16 v[126:129], v[144:147], v[176:179], v[126:129]
	s_waitcnt lgkmcnt(4)
	v_mfma_f32_16x16x32_bf16 v[110:113], v[148:151], v[176:179], v[110:113]
	s_waitcnt lgkmcnt(3)
	v_mfma_f32_16x16x32_bf16 v[30:33], v[152:155], v[176:179], v[30:33]
	v_mfma_f32_16x16x32_bf16 v[122:125], v[144:147], v[180:183], v[122:125]
	v_mfma_f32_16x16x32_bf16 v[74:77], v[148:151], v[180:183], v[74:77]
	v_mfma_f32_16x16x32_bf16 v[26:29], v[152:155], v[180:183], v[26:29]
	s_waitcnt lgkmcnt(2)
	v_mfma_f32_16x16x32_bf16 v[118:121], v[144:147], v[168:171], v[118:121]
	v_mfma_f32_16x16x32_bf16 v[38:41], v[148:151], v[168:171], v[38:41]
	v_mfma_f32_16x16x32_bf16 v[22:25], v[152:155], v[168:171], v[22:25]
	s_waitcnt lgkmcnt(1)
	v_mfma_f32_16x16x32_bf16 v[114:117], v[144:147], v[172:175], v[114:117]
	v_mfma_f32_16x16x32_bf16 v[34:37], v[148:151], v[172:175], v[34:37]
	v_mfma_f32_16x16x32_bf16 v[18:21], v[152:155], v[172:175], v[18:21]
	s_waitcnt lgkmcnt(0)
	v_mfma_f32_16x16x32_bf16 v[14:17], v[156:159], v[176:179], v[14:17]
	s_barrier
	v_mfma_f32_16x16x32_bf16 v[10:13], v[156:159], v[180:183], v[10:13]
	s_waitcnt vmcnt(8)
	ds_write_b128 v130, v[46:49]
	ds_write_b128 v130, v[54:57] offset:20480
	ds_write_b128 v130, v[62:65] offset:5120
	ds_write_b128 v130, v[70:73] offset:25600
	ds_write_b128 v130, v[82:85] offset:10240
	ds_write_b128 v130, v[90:93] offset:30720
	ds_write_b128 v130, v[98:101] offset:15360
	ds_write_b128 v130, v[106:109] offset:35840
	v_mfma_f32_16x16x32_bf16 v[6:9], v[156:159], v[168:171], v[6:9]
	v_mfma_f32_16x16x32_bf16 v[2:5], v[156:159], v[172:175], v[2:5]
	s_waitcnt lgkmcnt(0)
	s_barrier
	ds_read_b128 v[144:147], v131 offset:20480
	ds_read_b128 v[160:163], v238
	ds_read_b128 v[164:167], v238 offset:2560
	ds_read_b128 v[168:171], v238 offset:5120
	ds_read_b128 v[172:175], v238 offset:7680
	ds_read_b128 v[148:151], v131 offset:23040
	ds_read_b128 v[152:155], v131 offset:25600
	ds_read_b128 v[156:159], v131 offset:28160
	ds_read_b128 v[176:179], v238 offset:64
	ds_read_b128 v[180:183], v238 offset:2624
	s_cbranch_scc1 .LBB0_200
	v_add_co_u32_e32 v46, vcc, 0x4200000, v138
	s_nop 1
	v_addc_co_u32_e32 v47, vcc, 0, v139, vcc
	v_add_co_u32_e32 v54, vcc, 0xb3a0000, v136
	global_load_dwordx4 v[46:49], v[46:47], off offset:384
	s_nop 0
	v_addc_co_u32_e32 v55, vcc, 0, v137, vcc
	v_add_co_u32_e32 v62, vcc, 0x4211000, v138
	global_load_dwordx4 v[54:57], v[54:55], off offset:384
	s_nop 0
	v_addc_co_u32_e32 v63, vcc, 0, v139, vcc
	v_add_co_u32_e32 v70, vcc, 0xb3b1000, v136
	global_load_dwordx4 v[62:65], v[62:63], off offset:384
	s_nop 0
	v_addc_co_u32_e32 v71, vcc, 0, v137, vcc
	v_add_co_u32_e32 v82, vcc, 0x4222000, v138
	global_load_dwordx4 v[70:73], v[70:71], off offset:384
	s_nop 0
	v_addc_co_u32_e32 v83, vcc, 0, v139, vcc
	v_add_co_u32_e32 v90, vcc, 0xb3c2000, v136
	global_load_dwordx4 v[82:85], v[82:83], off offset:384
	s_nop 0
	v_addc_co_u32_e32 v91, vcc, 0, v137, vcc
	v_add_co_u32_e32 v98, vcc, 0x4233000, v138
	global_load_dwordx4 v[90:93], v[90:91], off offset:384
	s_nop 0
	v_addc_co_u32_e32 v99, vcc, 0, v139, vcc
	v_add_co_u32_e32 v106, vcc, 0xb3d3000, v136
	global_load_dwordx4 v[98:101], v[98:99], off offset:384
	s_nop 0
	v_addc_co_u32_e32 v107, vcc, 0, v137, vcc
	global_load_dwordx4 v[106:109], v[106:107], off offset:384
	s_branch .LBB0_200

; DEV f32x4 mfma16(bf16x8 a, bf16x8 b, f32x4 c) { return __builtin_amdgcn_mfma_f32_16x16x32_bf16(a, b, c, 0, 0, 0); }
; #define G_LOAD(RA, RB, KT) { _Pragma("unroll") for (int i = 0; i < 4; i++) { \
;       RA[i] = *(const u32x4*)(Ap + (size_t)(i * 32) * lda + (KT) * 64); RB[i] = *(const u32x4*)(Bp + (size_t)(i * 32) * ldb + (KT) * 64); } }
; #define G_STORE(RA, RB) { _Pragma("unroll") for (int i = 0; i < 4; i++) { \
;       *(u32x4*)(As + (lrow + i * 32) * GLD + lcc * 8) = RA[i]; *(u32x4*)(Bs + (lrow + i * 32) * GLD + lcc * 8) = RB[i]; } }
; template <int TI, int TJ, int KS>
; DEV void mfma_lds(const bf16_t* Arows, int lda, const bf16_t* Brows, int ldb, int i0, int j0, f32x4 (&acc)[TI][TJ]) {
;     ...
;   for (int ks = 0; ks < KS; ks++) {
;     bf16x8 af[TI], bfr[TJ];
; #pragma unroll
;     for (int i = 0; i < TI; i++) af[i] = *(const bf16x8*)(Arows + (i0 + i * 16 + l15) * lda + ks * 32 + quad * 8);
; #pragma unroll
;     for (int j = 0; j < TJ; j++) bfr[j] = *(const bf16x8*)(Brows + (j0 + j * 16 + l15) * ldb + ks * 32 + quad * 8);
; #pragma unroll
;     for (int i = 0; i < TI; i++)
; #pragma unroll
;       for (int j = 0; j < TJ; j++) acc[i][j] = mfma16(af[i], bfr[j], acc[i][j]);
;   }
; template <class Epi>
; DEV void gemm_tile(const bf16_t* __restrict__ A, int lda, const bf16_t* __restrict__ Bt, int ldb, int K, int m0, int n0,
;                    Epi& epi, char* smem) {
;     ...
;   for (int kt = 0; kt < nk; kt += 2) {
;     __syncthreads();
;     G_STORE(ra0, rb0);
;     __syncthreads();
;     if (kt + 2 < nk) G_LOAD(ra0, rb0, kt + 2);
;     mfma_lds<4, 4, 2>(Bs, GLD, As, GLD, wn * 64, wm * 64, acc);
;     __syncthreads();
;     G_STORE(ra1, rb1);
;     __syncthreads();
;     if (kt + 3 < nk) G_LOAD(ra1, rb1, kt + 3);
;     mfma_lds<4, 4, 2>(Bs, GLD, As, GLD, wn * 64, wm * 64, acc);
;   }
.LBB0_324:
	v_lshl_add_u64 v[132:133], v[132:133], 0, s[34:35]
	v_lshl_add_u64 v[134:135], v[134:135], 0, s[34:35]
	s_and_b64 vcc, exec, s[6:7]
	s_waitcnt lgkmcnt(8)
	v_mfma_f32_16x16x32_bf16 v[62:65], v[144:147], v[160:163], v[62:65]
	s_waitcnt lgkmcnt(7)
	v_mfma_f32_16x16x32_bf16 v[58:61], v[144:147], v[164:167], v[58:61]
	s_waitcnt lgkmcnt(6)
	v_mfma_f32_16x16x32_bf16 v[54:57], v[144:147], v[168:171], v[54:57]
	s_waitcnt lgkmcnt(5)
	v_mfma_f32_16x16x32_bf16 v[50:53], v[144:147], v[172:175], v[50:53]
	ds_read_b128 v[144:147], v131 offset:20544
	s_waitcnt lgkmcnt(5)
	v_mfma_f32_16x16x32_bf16 v[46:49], v[148:151], v[160:163], v[46:49]
	v_mfma_f32_16x16x32_bf16 v[42:45], v[148:151], v[164:167], v[42:45]
	v_mfma_f32_16x16x32_bf16 v[38:41], v[148:151], v[168:171], v[38:41]
	v_mfma_f32_16x16x32_bf16 v[34:37], v[148:151], v[172:175], v[34:37]
	ds_read_b128 v[148:151], v131 offset:23104
	s_waitcnt lgkmcnt(5)
	v_mfma_f32_16x16x32_bf16 v[30:33], v[152:155], v[160:163], v[30:33]
	v_mfma_f32_16x16x32_bf16 v[26:29], v[152:155], v[164:167], v[26:29]
	v_mfma_f32_16x16x32_bf16 v[22:25], v[152:155], v[168:171], v[22:25]
	v_mfma_f32_16x16x32_bf16 v[18:21], v[152:155], v[172:175], v[18:21]
	ds_read_b128 v[152:155], v131 offset:25664
	s_waitcnt lgkmcnt(5)
	v_mfma_f32_16x16x32_bf16 v[6:9], v[156:159], v[168:171], v[6:9]
	v_mfma_f32_16x16x32_bf16 v[2:5], v[156:159], v[172:175], v[2:5]
	ds_read_b128 v[168:171], v238 offset:5184
	ds_read_b128 v[172:175], v238 offset:7744
	v_mfma_f32_16x16x32_bf16 v[14:17], v[156:159], v[160:163], v[14:17]
	v_mfma_f32_16x16x32_bf16 v[10:13], v[156:159], v[164:167], v[10:13]
	ds_read_b128 v[156:159], v131 offset:28224
	s_waitcnt lgkmcnt(5)
	v_mfma_f32_16x16x32_bf16 v[62:65], v[144:147], v[176:179], v[62:65]
	s_waitcnt lgkmcnt(4)
	v_mfma_f32_16x16x32_bf16 v[46:49], v[148:151], v[176:179], v[46:49]
	s_waitcnt lgkmcnt(3)
	v_mfma_f32_16x16x32_bf16 v[30:33], v[152:155], v[176:179], v[30:33]
	v_mfma_f32_16x16x32_bf16 v[58:61], v[144:147], v[180:183], v[58:61]
	v_mfma_f32_16x16x32_bf16 v[42:45], v[148:151], v[180:183], v[42:45]
	v_mfma_f32_16x16x32_bf16 v[26:29], v[152:155], v[180:183], v[26:29]
	s_waitcnt lgkmcnt(2)
	v_mfma_f32_16x16x32_bf16 v[54:57], v[144:147], v[168:171], v[54:57]
	v_mfma_f32_16x16x32_bf16 v[38:41], v[148:151], v[168:171], v[38:41]
	v_mfma_f32_16x16x32_bf16 v[22:25], v[152:155], v[168:171], v[22:25]
	s_waitcnt lgkmcnt(1)
	v_mfma_f32_16x16x32_bf16 v[50:53], v[144:147], v[172:175], v[50:53]
	v_mfma_f32_16x16x32_bf16 v[34:37], v[148:151], v[172:175], v[34:37]
	v_mfma_f32_16x16x32_bf16 v[18:21], v[152:155], v[172:175], v[18:21]
	s_waitcnt lgkmcnt(0)
	v_mfma_f32_16x16x32_bf16 v[14:17], v[156:159], v[176:179], v[14:17]
	v_mfma_f32_16x16x32_bf16 v[10:13], v[156:159], v[180:183], v[10:13]
	v_mfma_f32_16x16x32_bf16 v[6:9], v[156:159], v[168:171], v[6:9]
	v_mfma_f32_16x16x32_bf16 v[2:5], v[156:159], v[172:175], v[2:5]
	s_cbranch_vccnz .LBB0_329
.LBB0_325:
	s_add_i32 s1, s1, 2
	s_cmp_gt_u32 s1, 13
	s_cselect_b64 s[6:7], -1, 0
	s_and_b64 vcc, exec, s[6:7]
	v_lshl_add_u64 v[138:139], v[134:135], 0, v[0:1]
	v_lshl_add_u64 v[136:137], v[132:133], 0, v[0:1]
	s_waitcnt lgkmcnt(0)
	s_barrier
	s_waitcnt vmcnt(8)
	ds_write_b128 v130, v[66:69]
	ds_write_b128 v130, v[74:77] offset:20480
	ds_write_b128 v130, v[82:85] offset:5120
	ds_write_b128 v130, v[90:93] offset:25600
	ds_write_b128 v130, v[98:101] offset:10240
	ds_write_b128 v130, v[106:109] offset:30720
	ds_write_b128 v130, v[114:117] offset:15360
	ds_write_b128 v130, v[122:125] offset:35840
	s_waitcnt lgkmcnt(0)
	s_barrier
	v_mov_b32_e32 v131, v195
	v_and_b32_e32 v143, 15, v131
	v_or_b32_e32 v144, v143, v142
	v_and_b32_e32 v148, 48, v131
	v_mul_u32_u24_e32 v131, 0x50, v144
	v_lshl_add_u32 v131, v131, 1, v148
	v_or_b32_e32 v143, v143, v141
	v_mad_u32_u24 v238, v143, s36, v148
	ds_read_b128 v[144:147], v131 offset:20480
	ds_read_b128 v[160:163], v238
	ds_read_b128 v[164:167], v238 offset:2560
	ds_read_b128 v[168:171], v238 offset:5120
	ds_read_b128 v[172:175], v238 offset:7680
	ds_read_b128 v[148:151], v131 offset:23040
	ds_read_b128 v[152:155], v131 offset:25600
	ds_read_b128 v[156:159], v131 offset:28160
	ds_read_b128 v[176:179], v238 offset:64
	ds_read_b128 v[180:183], v238 offset:2624
	s_cbranch_vccnz .Lgw_skip_2
	v_add_co_u32_e32 v66, vcc, 0x4200000, v138
	s_nop 1
	v_addc_co_u32_e32 v67, vcc, 0, v139, vcc
	v_add_co_u32_e32 v74, vcc, 0xa900000, v136
	global_load_dwordx4 v[66:69], v[66:67], off offset:256
	s_nop 0
	v_addc_co_u32_e32 v75, vcc, 0, v137, vcc
	v_add_co_u32_e32 v82, vcc, 0x4211000, v138
	global_load_dwordx4 v[74:77], v[74:75], off offset:256
	s_nop 0
	v_addc_co_u32_e32 v83, vcc, 0, v139, vcc
	v_add_co_u32_e32 v90, vcc, 0xa911000, v136
	global_load_dwordx4 v[82:85], v[82:83], off offset:256
	s_nop 0
	v_addc_co_u32_e32 v91, vcc, 0, v137, vcc
	v_add_co_u32_e32 v98, vcc, 0x4222000, v138
	global_load_dwordx4 v[90:93], v[90:91], off offset:256
	s_nop 0
	v_addc_co_u32_e32 v99, vcc, 0, v139, vcc
	v_add_co_u32_e32 v106, vcc, 0xa922000, v136
	global_load_dwordx4 v[98:101], v[98:99], off offset:256
	s_nop 0
	v_addc_co_u32_e32 v107, vcc, 0, v137, vcc
	v_add_co_u32_e32 v114, vcc, 0x4233000, v138
	global_load_dwordx4 v[106:109], v[106:107], off offset:256
	s_nop 0
	v_addc_co_u32_e32 v115, vcc, 0, v139, vcc
	v_add_co_u32_e32 v122, vcc, 0xa933000, v136
	global_load_dwordx4 v[114:117], v[114:115], off offset:256
	s_nop 0
	v_addc_co_u32_e32 v123, vcc, 0, v137, vcc
	global_load_dwordx4 v[122:125], v[122:123], off offset:256
; DEV f32x4 mfma16(bf16x8 a, bf16x8 b, f32x4 c) { return __builtin_amdgcn_mfma_f32_16x16x32_bf16(a, b, c, 0, 0, 0); }
; #define G_LOAD(RA, RB, KT) { _Pragma("unroll") for (int i = 0; i < 4; i++) { \
;       RA[i] = *(const u32x4*)(Ap + (size_t)(i * 32) * lda + (KT) * 64); RB[i] = *(const u32x4*)(Bp + (size_t)(i * 32) * ldb + (KT) * 64); } }
; #define G_STORE(RA, RB) { _Pragma("unroll") for (int i = 0; i < 4; i++) { \
;       *(u32x4*)(As + (lrow + i * 32) * GLD + lcc * 8) = RA[i]; *(u32x4*)(Bs + (lrow + i * 32) * GLD + lcc * 8) = RB[i]; } }
; template <int TI, int TJ, int KS>
; DEV void mfma_lds(const bf16_t* Arows, int lda, const bf16_t* Brows, int ldb, int i0, int j0, f32x4 (&acc)[TI][TJ]) {
;     ...
;   for (int ks = 0; ks < KS; ks++) {
;     bf16x8 af[TI], bfr[TJ];
; #pragma unroll
;     for (int i = 0; i < TI; i++) af[i] = *(const bf16x8*)(Arows + (i0 + i * 16 + l15) * lda + ks * 32 + quad * 8);
; #pragma unroll
;     for (int j = 0; j < TJ; j++) bfr[j] = *(const bf16x8*)(Brows + (j0 + j * 16 + l15) * ldb + ks * 32 + quad * 8);
; #pragma unroll
;     for (int i = 0; i < TI; i++)
; #pragma unroll
;       for (int j = 0; j < TJ; j++) acc[i][j] = mfma16(af[i], bfr[j], acc[i][j]);
;   }
; template <class Epi>
; DEV void gemm_tile(const bf16_t* __restrict__ A, int lda, const bf16_t* __restrict__ Bt, int ldb, int K, int m0, int n0,
;                    Epi& epi, char* smem) {
;     ...
;   for (int kt = 0; kt < nk; kt += 2) {
;     __syncthreads();
;     G_STORE(ra0, rb0);
;     __syncthreads();
;     if (kt + 2 < nk) G_LOAD(ra0, rb0, kt + 2);
;     mfma_lds<4, 4, 2>(Bs, GLD, As, GLD, wn * 64, wm * 64, acc);
;     __syncthreads();
;     G_STORE(ra1, rb1);
;     __syncthreads();
;     if (kt + 3 < nk) G_LOAD(ra1, rb1, kt + 3);
;     mfma_lds<4, 4, 2>(Bs, GLD, As, GLD, wn * 64, wm * 64, acc);
;   }
.LBB0_327:
	s_cmp_gt_u32 s1, 12
	s_waitcnt lgkmcnt(8)
	v_mfma_f32_16x16x32_bf16 v[62:65], v[144:147], v[160:163], v[62:65]
	s_waitcnt lgkmcnt(7)
	v_mfma_f32_16x16x32_bf16 v[58:61], v[144:147], v[164:167], v[58:61]
	s_waitcnt lgkmcnt(6)
	v_mfma_f32_16x16x32_bf16 v[54:57], v[144:147], v[168:171], v[54:57]
	s_waitcnt lgkmcnt(5)
	v_mfma_f32_16x16x32_bf16 v[50:53], v[144:147], v[172:175], v[50:53]
	ds_read_b128 v[144:147], v131 offset:20544
	s_waitcnt lgkmcnt(5)
	v_mfma_f32_16x16x32_bf16 v[46:49], v[148:151], v[160:163], v[46:49]
	v_mfma_f32_16x16x32_bf16 v[42:45], v[148:151], v[164:167], v[42:45]
	v_mfma_f32_16x16x32_bf16 v[38:41], v[148:151], v[168:171], v[38:41]
	v_mfma_f32_16x16x32_bf16 v[34:37], v[148:151], v[172:175], v[34:37]
	ds_read_b128 v[148:151], v131 offset:23104
	s_waitcnt lgkmcnt(5)
	v_mfma_f32_16x16x32_bf16 v[30:33], v[152:155], v[160:163], v[30:33]
	v_mfma_f32_16x16x32_bf16 v[26:29], v[152:155], v[164:167], v[26:29]
	v_mfma_f32_16x16x32_bf16 v[22:25], v[152:155], v[168:171], v[22:25]
	v_mfma_f32_16x16x32_bf16 v[18:21], v[152:155], v[172:175], v[18:21]
	ds_read_b128 v[152:155], v131 offset:25664
	s_waitcnt lgkmcnt(5)
	v_mfma_f32_16x16x32_bf16 v[6:9], v[156:159], v[168:171], v[6:9]
	v_mfma_f32_16x16x32_bf16 v[2:5], v[156:159], v[172:175], v[2:5]
	ds_read_b128 v[168:171], v238 offset:5184
	ds_read_b128 v[172:175], v238 offset:7744
	v_mfma_f32_16x16x32_bf16 v[14:17], v[156:159], v[160:163], v[14:17]
	v_mfma_f32_16x16x32_bf16 v[10:13], v[156:159], v[164:167], v[10:13]
	ds_read_b128 v[156:159], v131 offset:28224
	s_waitcnt lgkmcnt(5)
	v_mfma_f32_16x16x32_bf16 v[62:65], v[144:147], v[176:179], v[62:65]
	s_waitcnt lgkmcnt(4)
	v_mfma_f32_16x16x32_bf16 v[46:49], v[148:151], v[176:179], v[46:49]
	s_waitcnt lgkmcnt(3)
	v_mfma_f32_16x16x32_bf16 v[30:33], v[152:155], v[176:179], v[30:33]
	v_mfma_f32_16x16x32_bf16 v[58:61], v[144:147], v[180:183], v[58:61]
	v_mfma_f32_16x16x32_bf16 v[42:45], v[148:151], v[180:183], v[42:45]
	v_mfma_f32_16x16x32_bf16 v[26:29], v[152:155], v[180:183], v[26:29]
	s_waitcnt lgkmcnt(2)
	v_mfma_f32_16x16x32_bf16 v[54:57], v[144:147], v[168:171], v[54:57]
	v_mfma_f32_16x16x32_bf16 v[38:41], v[148:151], v[168:171], v[38:41]
	v_mfma_f32_16x16x32_bf16 v[22:25], v[152:155], v[168:171], v[22:25]
	s_waitcnt lgkmcnt(1)
	v_mfma_f32_16x16x32_bf16 v[50:53], v[144:147], v[172:175], v[50:53]
	v_mfma_f32_16x16x32_bf16 v[34:37], v[148:151], v[172:175], v[34:37]
	v_mfma_f32_16x16x32_bf16 v[18:21], v[152:155], v[172:175], v[18:21]
	s_waitcnt lgkmcnt(0)
	v_mfma_f32_16x16x32_bf16 v[14:17], v[156:159], v[176:179], v[14:17]
	s_barrier
	v_mfma_f32_16x16x32_bf16 v[10:13], v[156:159], v[180:183], v[10:13]
	s_waitcnt vmcnt(8)
	ds_write_b128 v130, v[70:73]
	ds_write_b128 v130, v[78:81] offset:20480
	ds_write_b128 v130, v[86:89] offset:5120
	ds_write_b128 v130, v[94:97] offset:25600
	ds_write_b128 v130, v[102:105] offset:10240
	ds_write_b128 v130, v[110:113] offset:30720
	ds_write_b128 v130, v[118:121] offset:15360
	ds_write_b128 v130, v[126:129] offset:35840
	v_mfma_f32_16x16x32_bf16 v[6:9], v[156:159], v[168:171], v[6:9]
	v_mfma_f32_16x16x32_bf16 v[2:5], v[156:159], v[172:175], v[2:5]
	s_waitcnt lgkmcnt(0)
	s_barrier
	ds_read_b128 v[144:147], v131 offset:20480
	ds_read_b128 v[160:163], v238
	ds_read_b128 v[164:167], v238 offset:2560
	ds_read_b128 v[168:171], v238 offset:5120
	ds_read_b128 v[172:175], v238 offset:7680
	ds_read_b128 v[148:151], v131 offset:23040
	ds_read_b128 v[152:155], v131 offset:25600
	ds_read_b128 v[156:159], v131 offset:28160
	ds_read_b128 v[176:179], v238 offset:64
	ds_read_b128 v[180:183], v238 offset:2624
	s_cbranch_scc1 .LBB0_324
	v_add_co_u32_e32 v70, vcc, 0x4200000, v138
	s_nop 1
	v_addc_co_u32_e32 v71, vcc, 0, v139, vcc
	v_add_co_u32_e32 v78, vcc, 0xa900000, v136
	global_load_dwordx4 v[70:73], v[70:71], off offset:384
	s_nop 0
	v_addc_co_u32_e32 v79, vcc, 0, v137, vcc
	v_add_co_u32_e32 v86, vcc, 0x4211000, v138
	global_load_dwordx4 v[78:81], v[78:79], off offset:384
	s_nop 0
	v_addc_co_u32_e32 v87, vcc, 0, v139, vcc
	v_add_co_u32_e32 v94, vcc, 0xa911000, v136
	global_load_dwordx4 v[86:89], v[86:87], off offset:384
	s_nop 0
	v_addc_co_u32_e32 v95, vcc, 0, v137, vcc
	v_add_co_u32_e32 v102, vcc, 0x4222000, v138
	global_load_dwordx4 v[94:97], v[94:95], off offset:384
	s_nop 0
	v_addc_co_u32_e32 v103, vcc, 0, v139, vcc
	v_add_co_u32_e32 v110, vcc, 0xa922000, v136
	global_load_dwordx4 v[102:105], v[102:103], off offset:384
	s_nop 0
	v_addc_co_u32_e32 v111, vcc, 0, v137, vcc
	v_add_co_u32_e32 v118, vcc, 0x4233000, v138
	global_load_dwordx4 v[110:113], v[110:111], off offset:384
	s_nop 0
	v_addc_co_u32_e32 v119, vcc, 0, v139, vcc
	v_add_co_u32_e32 v126, vcc, 0xa933000, v136
	global_load_dwordx4 v[118:121], v[118:119], off offset:384
	s_nop 0
	v_addc_co_u32_e32 v127, vcc, 0, v137, vcc
	global_load_dwordx4 v[126:129], v[126:127], off offset:384
	s_branch .LBB0_324

; DEV f32x4 mfma16(bf16x8 a, bf16x8 b, f32x4 c) { return __builtin_amdgcn_mfma_f32_16x16x32_bf16(a, b, c, 0, 0, 0); }
; #define G_LOAD(RA, RB, KT) { _Pragma("unroll") for (int i = 0; i < 4; i++) { \
;       RA[i] = *(const u32x4*)(Ap + (size_t)(i * 32) * lda + (KT) * 64); RB[i] = *(const u32x4*)(Bp + (size_t)(i * 32) * ldb + (KT) * 64); } }
; #define G_STORE(RA, RB) { _Pragma("unroll") for (int i = 0; i < 4; i++) { \
;       *(u32x4*)(As + (lrow + i * 32) * GLD + lcc * 8) = RA[i]; *(u32x4*)(Bs + (lrow + i * 32) * GLD + lcc * 8) = RB[i]; } }
; template <int TI, int TJ, int KS>
; DEV void mfma_lds(const bf16_t* Arows, int lda, const bf16_t* Brows, int ldb, int i0, int j0, f32x4 (&acc)[TI][TJ]) {
;     ...
;   for (int ks = 0; ks < KS; ks++) {
;     bf16x8 af[TI], bfr[TJ];
; #pragma unroll
;     for (int i = 0; i < TI; i++) af[i] = *(const bf16x8*)(Arows + (i0 + i * 16 + l15) * lda + ks * 32 + quad * 8);
; #pragma unroll
;     for (int j = 0; j < TJ; j++) bfr[j] = *(const bf16x8*)(Brows + (j0 + j * 16 + l15) * ldb + ks * 32 + quad * 8);
; #pragma unroll
;     for (int i = 0; i < TI; i++)
; #pragma unroll
;       for (int j = 0; j < TJ; j++) acc[i][j] = mfma16(af[i], bfr[j], acc[i][j]);
;   }
; template <class Epi>
; DEV void gemm_tile(const bf16_t* __restrict__ A, int lda, const bf16_t* __restrict__ Bt, int ldb, int K, int m0, int n0,
;                    Epi& epi, char* smem) {
;     ...
;   for (int kt = 0; kt < nk; kt += 2) {
;     __syncthreads();
;     G_STORE(ra0, rb0);
;     __syncthreads();
;     if (kt + 2 < nk) G_LOAD(ra0, rb0, kt + 2);
;     mfma_lds<4, 4, 2>(Bs, GLD, As, GLD, wn * 64, wm * 64, acc);
;     __syncthreads();
;     G_STORE(ra1, rb1);
;     __syncthreads();
;     if (kt + 3 < nk) G_LOAD(ra1, rb1, kt + 3);
;     mfma_lds<4, 4, 2>(Bs, GLD, As, GLD, wn * 64, wm * 64, acc);
;   }
.LBB0_646:
	v_lshl_add_u64 v[136:137], v[136:137], 0, s[34:35]
	v_lshl_add_u64 v[138:139], v[138:139], 0, s[34:35]
	s_andn2_b64 vcc, exec, s[8:9]
	s_waitcnt lgkmcnt(8)
	v_mfma_f32_16x16x32_bf16 v[106:109], v[148:151], v[164:167], v[106:109]
	s_waitcnt lgkmcnt(7)
	v_mfma_f32_16x16x32_bf16 v[122:125], v[148:151], v[168:171], v[122:125]
	s_waitcnt lgkmcnt(6)
	v_mfma_f32_16x16x32_bf16 v[114:117], v[148:151], v[172:175], v[114:117]
	s_waitcnt lgkmcnt(5)
	v_mfma_f32_16x16x32_bf16 v[110:113], v[148:151], v[176:179], v[110:113]
	ds_read_b128 v[148:151], v147 offset:20544
	s_waitcnt lgkmcnt(5)
	v_mfma_f32_16x16x32_bf16 v[102:105], v[152:155], v[164:167], v[102:105]
	v_mfma_f32_16x16x32_bf16 v[94:97], v[152:155], v[168:171], v[94:97]
	v_mfma_f32_16x16x32_bf16 v[86:89], v[152:155], v[172:175], v[86:89]
	v_mfma_f32_16x16x32_bf16 v[78:81], v[152:155], v[176:179], v[78:81]
	ds_read_b128 v[152:155], v147 offset:23104
	s_waitcnt lgkmcnt(5)
	v_mfma_f32_16x16x32_bf16 v[82:85], v[156:159], v[164:167], v[82:85]
	v_mfma_f32_16x16x32_bf16 v[74:77], v[156:159], v[168:171], v[74:77]
	v_mfma_f32_16x16x32_bf16 v[70:73], v[156:159], v[172:175], v[70:73]
	v_mfma_f32_16x16x32_bf16 v[66:69], v[156:159], v[176:179], v[66:69]
	ds_read_b128 v[156:159], v147 offset:25664
	s_waitcnt lgkmcnt(5)
	v_mfma_f32_16x16x32_bf16 v[126:129], v[160:163], v[172:175], v[126:129]
	v_mfma_f32_16x16x32_bf16 v[118:121], v[160:163], v[176:179], v[118:121]
	ds_read_b128 v[172:175], v238 offset:5184
	ds_read_b128 v[176:179], v238 offset:7744
	v_mfma_f32_16x16x32_bf16 v[98:101], v[160:163], v[164:167], v[98:101]
	v_mfma_f32_16x16x32_bf16 v[90:93], v[160:163], v[168:171], v[90:93]
	ds_read_b128 v[160:163], v147 offset:28224
	s_waitcnt lgkmcnt(5)
	v_mfma_f32_16x16x32_bf16 v[106:109], v[148:151], v[180:183], v[106:109]
	s_waitcnt lgkmcnt(4)
	v_mfma_f32_16x16x32_bf16 v[102:105], v[152:155], v[180:183], v[102:105]
	s_waitcnt lgkmcnt(3)
	v_mfma_f32_16x16x32_bf16 v[82:85], v[156:159], v[180:183], v[82:85]
	v_mfma_f32_16x16x32_bf16 v[122:125], v[148:151], v[184:187], v[122:125]
	v_mfma_f32_16x16x32_bf16 v[94:97], v[152:155], v[184:187], v[94:97]
	v_mfma_f32_16x16x32_bf16 v[74:77], v[156:159], v[184:187], v[74:77]
	s_waitcnt lgkmcnt(2)
	v_mfma_f32_16x16x32_bf16 v[114:117], v[148:151], v[172:175], v[114:117]
	v_mfma_f32_16x16x32_bf16 v[86:89], v[152:155], v[172:175], v[86:89]
	v_mfma_f32_16x16x32_bf16 v[70:73], v[156:159], v[172:175], v[70:73]
	s_waitcnt lgkmcnt(1)
	v_mfma_f32_16x16x32_bf16 v[110:113], v[148:151], v[176:179], v[110:113]
	v_mfma_f32_16x16x32_bf16 v[78:81], v[152:155], v[176:179], v[78:81]
	v_mfma_f32_16x16x32_bf16 v[66:69], v[156:159], v[176:179], v[66:69]
	s_waitcnt lgkmcnt(0)
	v_mfma_f32_16x16x32_bf16 v[98:101], v[160:163], v[180:183], v[98:101]
	v_mfma_f32_16x16x32_bf16 v[90:93], v[160:163], v[184:187], v[90:93]
	v_mfma_f32_16x16x32_bf16 v[126:129], v[160:163], v[172:175], v[126:129]
	v_mfma_f32_16x16x32_bf16 v[118:121], v[160:163], v[176:179], v[118:121]
	s_cbranch_vccz .LBB0_642
.LBB0_647:
	s_add_i32 s14, s14, 2
	s_cmp_gt_u32 s14, 13
	s_cselect_b64 s[8:9], -1, 0
	s_and_b64 vcc, exec, s[8:9]
	v_lshl_add_u64 v[142:143], v[138:139], 0, v[0:1]
	v_lshl_add_u64 v[140:141], v[136:137], 0, v[0:1]
	s_waitcnt lgkmcnt(0)
	s_barrier
	s_waitcnt vmcnt(8)
	ds_write_b128 v134, v[2:5]
	ds_write_b128 v134, v[10:13] offset:20480
	ds_write_b128 v134, v[18:21] offset:5120
	ds_write_b128 v134, v[26:29] offset:25600
	ds_write_b128 v134, v[34:37] offset:10240
	ds_write_b128 v134, v[42:45] offset:30720
	ds_write_b128 v134, v[50:53] offset:15360
	ds_write_b128 v134, v[58:61] offset:35840
	s_waitcnt lgkmcnt(0)
	s_barrier
	v_mov_b32_e32 v130, v195
	v_and_b32_e32 v135, 15, v130
	v_or_b32_e32 v131, v135, v144
	v_and_b32_e32 v148, 48, v130
	v_mul_u32_u24_e32 v130, 0x50, v131
	v_lshl_add_u32 v147, v130, 1, v148
	v_or_b32_e32 v135, v135, v146
	v_mad_u32_u24 v238, v135, s36, v148
	ds_read_b128 v[148:151], v147 offset:20480
	ds_read_b128 v[164:167], v238
	ds_read_b128 v[168:171], v238 offset:2560
	ds_read_b128 v[172:175], v238 offset:5120
	ds_read_b128 v[176:179], v238 offset:7680
	ds_read_b128 v[152:155], v147 offset:23040
	ds_read_b128 v[156:159], v147 offset:25600
	ds_read_b128 v[160:163], v147 offset:28160
	ds_read_b128 v[180:183], v238 offset:64
	ds_read_b128 v[184:187], v238 offset:2624
	s_cbranch_vccnz .Lgw_skip_3
	v_add_co_u32_e32 v2, vcc, 0x4200000, v142
	s_nop 1
	v_addc_co_u32_e32 v3, vcc, 0, v143, vcc
	v_add_co_u32_e32 v10, vcc, 0xb5c0000, v140
	global_load_dwordx4 v[2:5], v[2:3], off offset:256
	s_nop 0
	v_addc_co_u32_e32 v11, vcc, 0, v141, vcc
	v_add_co_u32_e32 v18, vcc, 0x4211000, v142
	global_load_dwordx4 v[10:13], v[10:11], off offset:256
	s_nop 0
	v_addc_co_u32_e32 v19, vcc, 0, v143, vcc
	v_add_co_u32_e32 v26, vcc, 0xb5d1000, v140
	global_load_dwordx4 v[18:21], v[18:19], off offset:256
	s_nop 0
	v_addc_co_u32_e32 v27, vcc, 0, v141, vcc
	v_add_co_u32_e32 v34, vcc, 0x4222000, v142
	global_load_dwordx4 v[26:29], v[26:27], off offset:256
	s_nop 0
	v_addc_co_u32_e32 v35, vcc, 0, v143, vcc
	v_add_co_u32_e32 v42, vcc, 0xb5e2000, v140
	global_load_dwordx4 v[34:37], v[34:35], off offset:256
	s_nop 0
	v_addc_co_u32_e32 v43, vcc, 0, v141, vcc
	v_add_co_u32_e32 v50, vcc, 0x4233000, v142
	global_load_dwordx4 v[42:45], v[42:43], off offset:256
	s_nop 0
	v_addc_co_u32_e32 v51, vcc, 0, v143, vcc
	v_add_co_u32_e32 v58, vcc, 0xb5f3000, v140
	global_load_dwordx4 v[50:53], v[50:51], off offset:256
	s_nop 0
	v_addc_co_u32_e32 v59, vcc, 0, v141, vcc
	global_load_dwordx4 v[58:61], v[58:59], off offset:256
; DEV f32x4 mfma16(bf16x8 a, bf16x8 b, f32x4 c) { return __builtin_amdgcn_mfma_f32_16x16x32_bf16(a, b, c, 0, 0, 0); }
; #define G_LOAD(RA, RB, KT) { _Pragma("unroll") for (int i = 0; i < 4; i++) { \
;       RA[i] = *(const u32x4*)(Ap + (size_t)(i * 32) * lda + (KT) * 64); RB[i] = *(const u32x4*)(Bp + (size_t)(i * 32) * ldb + (KT) * 64); } }
; #define G_STORE(RA, RB) { _Pragma("unroll") for (int i = 0; i < 4; i++) { \
;       *(u32x4*)(As + (lrow + i * 32) * GLD + lcc * 8) = RA[i]; *(u32x4*)(Bs + (lrow + i * 32) * GLD + lcc * 8) = RB[i]; } }
; template <int TI, int TJ, int KS>
; DEV void mfma_lds(const bf16_t* Arows, int lda, const bf16_t* Brows, int ldb, int i0, int j0, f32x4 (&acc)[TI][TJ]) {
;     ...
;   for (int ks = 0; ks < KS; ks++) {
;     bf16x8 af[TI], bfr[TJ];
; #pragma unroll
;     for (int i = 0; i < TI; i++) af[i] = *(const bf16x8*)(Arows + (i0 + i * 16 + l15) * lda + ks * 32 + quad * 8);
; #pragma unroll
;     for (int j = 0; j < TJ; j++) bfr[j] = *(const bf16x8*)(Brows + (j0 + j * 16 + l15) * ldb + ks * 32 + quad * 8);
; #pragma unroll
;     for (int i = 0; i < TI; i++)
; #pragma unroll
;       for (int j = 0; j < TJ; j++) acc[i][j] = mfma16(af[i], bfr[j], acc[i][j]);
;   }
; template <class Epi>
; DEV void gemm_tile(const bf16_t* __restrict__ A, int lda, const bf16_t* __restrict__ Bt, int ldb, int K, int m0, int n0,
;                    Epi& epi, char* smem) {
;     ...
;   for (int kt = 0; kt < nk; kt += 2) {
;     __syncthreads();
;     G_STORE(ra0, rb0);
;     __syncthreads();
;     if (kt + 2 < nk) G_LOAD(ra0, rb0, kt + 2);
;     mfma_lds<4, 4, 2>(Bs, GLD, As, GLD, wn * 64, wm * 64, acc);
;     __syncthreads();
;     G_STORE(ra1, rb1);
;     __syncthreads();
;     if (kt + 3 < nk) G_LOAD(ra1, rb1, kt + 3);
;     mfma_lds<4, 4, 2>(Bs, GLD, As, GLD, wn * 64, wm * 64, acc);
;   }
.LBB0_649:
	s_cmp_gt_u32 s14, 12
	s_waitcnt lgkmcnt(8)
	v_mfma_f32_16x16x32_bf16 v[106:109], v[148:151], v[164:167], v[106:109]
	s_waitcnt lgkmcnt(7)
	v_mfma_f32_16x16x32_bf16 v[122:125], v[148:151], v[168:171], v[122:125]
	s_waitcnt lgkmcnt(6)
	v_mfma_f32_16x16x32_bf16 v[114:117], v[148:151], v[172:175], v[114:117]
	s_waitcnt lgkmcnt(5)
	v_mfma_f32_16x16x32_bf16 v[110:113], v[148:151], v[176:179], v[110:113]
	ds_read_b128 v[148:151], v147 offset:20544
	s_waitcnt lgkmcnt(5)
	v_mfma_f32_16x16x32_bf16 v[102:105], v[152:155], v[164:167], v[102:105]
	v_mfma_f32_16x16x32_bf16 v[94:97], v[152:155], v[168:171], v[94:97]
	v_mfma_f32_16x16x32_bf16 v[86:89], v[152:155], v[172:175], v[86:89]
	v_mfma_f32_16x16x32_bf16 v[78:81], v[152:155], v[176:179], v[78:81]
	ds_read_b128 v[152:155], v147 offset:23104
	s_waitcnt lgkmcnt(5)
	v_mfma_f32_16x16x32_bf16 v[82:85], v[156:159], v[164:167], v[82:85]
	v_mfma_f32_16x16x32_bf16 v[74:77], v[156:159], v[168:171], v[74:77]
	v_mfma_f32_16x16x32_bf16 v[70:73], v[156:159], v[172:175], v[70:73]
	v_mfma_f32_16x16x32_bf16 v[66:69], v[156:159], v[176:179], v[66:69]
	ds_read_b128 v[156:159], v147 offset:25664
	s_waitcnt lgkmcnt(5)
	v_mfma_f32_16x16x32_bf16 v[126:129], v[160:163], v[172:175], v[126:129]
	v_mfma_f32_16x16x32_bf16 v[118:121], v[160:163], v[176:179], v[118:121]
	ds_read_b128 v[172:175], v238 offset:5184
	ds_read_b128 v[176:179], v238 offset:7744
	v_mfma_f32_16x16x32_bf16 v[98:101], v[160:163], v[164:167], v[98:101]
	v_mfma_f32_16x16x32_bf16 v[90:93], v[160:163], v[168:171], v[90:93]
	ds_read_b128 v[160:163], v147 offset:28224
	s_waitcnt lgkmcnt(5)
	v_mfma_f32_16x16x32_bf16 v[106:109], v[148:151], v[180:183], v[106:109]
	s_waitcnt lgkmcnt(4)
	v_mfma_f32_16x16x32_bf16 v[102:105], v[152:155], v[180:183], v[102:105]
	s_waitcnt lgkmcnt(3)
	v_mfma_f32_16x16x32_bf16 v[82:85], v[156:159], v[180:183], v[82:85]
	v_mfma_f32_16x16x32_bf16 v[122:125], v[148:151], v[184:187], v[122:125]
	v_mfma_f32_16x16x32_bf16 v[94:97], v[152:155], v[184:187], v[94:97]
	v_mfma_f32_16x16x32_bf16 v[74:77], v[156:159], v[184:187], v[74:77]
	s_waitcnt lgkmcnt(2)
	v_mfma_f32_16x16x32_bf16 v[114:117], v[148:151], v[172:175], v[114:117]
	v_mfma_f32_16x16x32_bf16 v[86:89], v[152:155], v[172:175], v[86:89]
	v_mfma_f32_16x16x32_bf16 v[70:73], v[156:159], v[172:175], v[70:73]
	s_waitcnt lgkmcnt(1)
	v_mfma_f32_16x16x32_bf16 v[110:113], v[148:151], v[176:179], v[110:113]
	v_mfma_f32_16x16x32_bf16 v[78:81], v[152:155], v[176:179], v[78:81]
	v_mfma_f32_16x16x32_bf16 v[66:69], v[156:159], v[176:179], v[66:69]
	s_waitcnt lgkmcnt(0)
	v_mfma_f32_16x16x32_bf16 v[98:101], v[160:163], v[180:183], v[98:101]
	s_barrier
	v_mfma_f32_16x16x32_bf16 v[90:93], v[160:163], v[184:187], v[90:93]
	s_waitcnt vmcnt(8)
	ds_write_b128 v134, v[6:9]
	ds_write_b128 v134, v[14:17] offset:20480
	ds_write_b128 v134, v[22:25] offset:5120
	ds_write_b128 v134, v[30:33] offset:25600
	ds_write_b128 v134, v[38:41] offset:10240
	ds_write_b128 v134, v[46:49] offset:30720
	ds_write_b128 v134, v[54:57] offset:15360
	ds_write_b128 v134, v[62:65] offset:35840
	v_mfma_f32_16x16x32_bf16 v[126:129], v[160:163], v[172:175], v[126:129]
	v_mfma_f32_16x16x32_bf16 v[118:121], v[160:163], v[176:179], v[118:121]
	s_waitcnt lgkmcnt(0)
	s_barrier
	ds_read_b128 v[148:151], v147 offset:20480
	ds_read_b128 v[164:167], v238
	ds_read_b128 v[168:171], v238 offset:2560
	ds_read_b128 v[172:175], v238 offset:5120
	ds_read_b128 v[176:179], v238 offset:7680
	ds_read_b128 v[152:155], v147 offset:23040
	ds_read_b128 v[156:159], v147 offset:25600
	ds_read_b128 v[160:163], v147 offset:28160
	ds_read_b128 v[180:183], v238 offset:64
	ds_read_b128 v[184:187], v238 offset:2624
	s_cbranch_scc1 .LBB0_646
	v_add_co_u32_e32 v6, vcc, 0x4200000, v142
	s_nop 1
	v_addc_co_u32_e32 v7, vcc, 0, v143, vcc
	v_add_co_u32_e32 v14, vcc, 0xb5c0000, v140
	global_load_dwordx4 v[6:9], v[6:7], off offset:384
	s_nop 0
	v_addc_co_u32_e32 v15, vcc, 0, v141, vcc
	v_add_co_u32_e32 v22, vcc, 0x4211000, v142
	global_load_dwordx4 v[14:17], v[14:15], off offset:384
	s_nop 0
	v_addc_co_u32_e32 v23, vcc, 0, v143, vcc
	v_add_co_u32_e32 v30, vcc, 0xb5d1000, v140
	global_load_dwordx4 v[22:25], v[22:23], off offset:384
	s_nop 0
	v_addc_co_u32_e32 v31, vcc, 0, v141, vcc
	v_add_co_u32_e32 v38, vcc, 0x4222000, v142
	global_load_dwordx4 v[30:33], v[30:31], off offset:384
	s_nop 0
	v_addc_co_u32_e32 v39, vcc, 0, v143, vcc
	v_add_co_u32_e32 v46, vcc, 0xb5e2000, v140
	global_load_dwordx4 v[38:41], v[38:39], off offset:384
	s_nop 0
	v_addc_co_u32_e32 v47, vcc, 0, v141, vcc
	v_add_co_u32_e32 v54, vcc, 0x4233000, v142
	global_load_dwordx4 v[46:49], v[46:47], off offset:384
	s_nop 0
	v_addc_co_u32_e32 v55, vcc, 0, v143, vcc
	v_add_co_u32_e32 v62, vcc, 0xb5f3000, v140
	global_load_dwordx4 v[54:57], v[54:55], off offset:384
	s_nop 0
	v_addc_co_u32_e32 v63, vcc, 0, v141, vcc
	global_load_dwordx4 v[62:65], v[62:63], off offset:384
	s_branch .LBB0_646

; DEV f32x4 mfma16(bf16x8 a, bf16x8 b, f32x4 c) { return __builtin_amdgcn_mfma_f32_16x16x32_bf16(a, b, c, 0, 0, 0); }
; #define G_LOAD(RA, RB, KT) { _Pragma("unroll") for (int i = 0; i < 4; i++) { \
;       RA[i] = *(const u32x4*)(Ap + (size_t)(i * 32) * lda + (KT) * 64); RB[i] = *(const u32x4*)(Bp + (size_t)(i * 32) * ldb + (KT) * 64); } }
; #define G_STORE(RA, RB) { _Pragma("unroll") for (int i = 0; i < 4; i++) { \
;       *(u32x4*)(As + (lrow + i * 32) * GLD + lcc * 8) = RA[i]; *(u32x4*)(Bs + (lrow + i * 32) * GLD + lcc * 8) = RB[i]; } }
; template <int TI, int TJ, int KS>
; DEV void mfma_lds(const bf16_t* Arows, int lda, const bf16_t* Brows, int ldb, int i0, int j0, f32x4 (&acc)[TI][TJ]) {
;     ...
;   for (int ks = 0; ks < KS; ks++) {
;     bf16x8 af[TI], bfr[TJ];
; #pragma unroll
;     for (int i = 0; i < TI; i++) af[i] = *(const bf16x8*)(Arows + (i0 + i * 16 + l15) * lda + ks * 32 + quad * 8);
; #pragma unroll
;     for (int j = 0; j < TJ; j++) bfr[j] = *(const bf16x8*)(Brows + (j0 + j * 16 + l15) * ldb + ks * 32 + quad * 8);
; #pragma unroll
;     for (int i = 0; i < TI; i++)
; #pragma unroll
;       for (int j = 0; j < TJ; j++) acc[i][j] = mfma16(af[i], bfr[j], acc[i][j]);
;   }
; template <class Epi>
; DEV void gemm_tile(const bf16_t* __restrict__ A, int lda, const bf16_t* __restrict__ Bt, int ldb, int K, int m0, int n0,
;                    Epi& epi, char* smem) {
;     ...
;   for (int kt = 0; kt < nk; kt += 2) {
;     __syncthreads();
;     G_STORE(ra0, rb0);
;     __syncthreads();
;     if (kt + 2 < nk) G_LOAD(ra0, rb0, kt + 2);
;     mfma_lds<4, 4, 2>(Bs, GLD, As, GLD, wn * 64, wm * 64, acc);
;     __syncthreads();
;     G_STORE(ra1, rb1);
;     __syncthreads();
;     if (kt + 3 < nk) G_LOAD(ra1, rb1, kt + 3);
;     mfma_lds<4, 4, 2>(Bs, GLD, As, GLD, wn * 64, wm * 64, acc);
;   }
.LBB0_670:
	v_lshl_add_u64 v[132:133], v[132:133], 0, s[34:35]
	v_lshl_add_u64 v[134:135], v[134:135], 0, s[34:35]
	s_and_b64 vcc, exec, s[8:9]
	s_waitcnt lgkmcnt(8)
	v_mfma_f32_16x16x32_bf16 v[126:129], v[144:147], v[160:163], v[126:129]
	s_waitcnt lgkmcnt(7)
	v_mfma_f32_16x16x32_bf16 v[122:125], v[144:147], v[164:167], v[122:125]
	s_waitcnt lgkmcnt(6)
	v_mfma_f32_16x16x32_bf16 v[118:121], v[144:147], v[168:171], v[118:121]
	s_waitcnt lgkmcnt(5)
	v_mfma_f32_16x16x32_bf16 v[114:117], v[144:147], v[172:175], v[114:117]
	ds_read_b128 v[144:147], v131 offset:20544
	s_waitcnt lgkmcnt(5)
	v_mfma_f32_16x16x32_bf16 v[110:113], v[148:151], v[160:163], v[110:113]
	v_mfma_f32_16x16x32_bf16 v[58:61], v[148:151], v[164:167], v[58:61]
	v_mfma_f32_16x16x32_bf16 v[38:41], v[148:151], v[168:171], v[38:41]
	v_mfma_f32_16x16x32_bf16 v[34:37], v[148:151], v[172:175], v[34:37]
	ds_read_b128 v[148:151], v131 offset:23104
	s_waitcnt lgkmcnt(5)
	v_mfma_f32_16x16x32_bf16 v[30:33], v[152:155], v[160:163], v[30:33]
	v_mfma_f32_16x16x32_bf16 v[26:29], v[152:155], v[164:167], v[26:29]
	v_mfma_f32_16x16x32_bf16 v[22:25], v[152:155], v[168:171], v[22:25]
	v_mfma_f32_16x16x32_bf16 v[18:21], v[152:155], v[172:175], v[18:21]
	ds_read_b128 v[152:155], v131 offset:25664
	s_waitcnt lgkmcnt(5)
	v_mfma_f32_16x16x32_bf16 v[6:9], v[156:159], v[168:171], v[6:9]
	v_mfma_f32_16x16x32_bf16 v[2:5], v[156:159], v[172:175], v[2:5]
	ds_read_b128 v[168:171], v238 offset:5184
	ds_read_b128 v[172:175], v238 offset:7744
	v_mfma_f32_16x16x32_bf16 v[14:17], v[156:159], v[160:163], v[14:17]
	v_mfma_f32_16x16x32_bf16 v[10:13], v[156:159], v[164:167], v[10:13]
	ds_read_b128 v[156:159], v131 offset:28224
	s_waitcnt lgkmcnt(5)
	v_mfma_f32_16x16x32_bf16 v[126:129], v[144:147], v[176:179], v[126:129]
	s_waitcnt lgkmcnt(4)
	v_mfma_f32_16x16x32_bf16 v[110:113], v[148:151], v[176:179], v[110:113]
	s_waitcnt lgkmcnt(3)
	v_mfma_f32_16x16x32_bf16 v[30:33], v[152:155], v[176:179], v[30:33]
	v_mfma_f32_16x16x32_bf16 v[122:125], v[144:147], v[180:183], v[122:125]
	v_mfma_f32_16x16x32_bf16 v[58:61], v[148:151], v[180:183], v[58:61]
	v_mfma_f32_16x16x32_bf16 v[26:29], v[152:155], v[180:183], v[26:29]
	s_waitcnt lgkmcnt(2)
	v_mfma_f32_16x16x32_bf16 v[118:121], v[144:147], v[168:171], v[118:121]
	v_mfma_f32_16x16x32_bf16 v[38:41], v[148:151], v[168:171], v[38:41]
	v_mfma_f32_16x16x32_bf16 v[22:25], v[152:155], v[168:171], v[22:25]
	s_waitcnt lgkmcnt(1)
	v_mfma_f32_16x16x32_bf16 v[114:117], v[144:147], v[172:175], v[114:117]
	v_mfma_f32_16x16x32_bf16 v[34:37], v[148:151], v[172:175], v[34:37]
	v_mfma_f32_16x16x32_bf16 v[18:21], v[152:155], v[172:175], v[18:21]
	s_waitcnt lgkmcnt(0)
	v_mfma_f32_16x16x32_bf16 v[14:17], v[156:159], v[176:179], v[14:17]
	v_mfma_f32_16x16x32_bf16 v[10:13], v[156:159], v[180:183], v[10:13]
	v_mfma_f32_16x16x32_bf16 v[6:9], v[156:159], v[168:171], v[6:9]
	v_mfma_f32_16x16x32_bf16 v[2:5], v[156:159], v[172:175], v[2:5]
	s_cbranch_vccnz .LBB0_675
.LBB0_671:
	s_add_i32 s15, s15, 2
	s_cmp_gt_u32 s15, 13
	s_cselect_b64 s[8:9], -1, 0
	s_and_b64 vcc, exec, s[8:9]
	v_lshl_add_u64 v[138:139], v[134:135], 0, v[0:1]
	v_lshl_add_u64 v[136:137], v[132:133], 0, v[0:1]
	s_waitcnt lgkmcnt(0)
	s_barrier
	s_waitcnt vmcnt(8)
	ds_write_b128 v130, v[42:45]
	ds_write_b128 v130, v[50:53] offset:20480
	ds_write_b128 v130, v[62:65] offset:5120
	ds_write_b128 v130, v[70:73] offset:25600
	ds_write_b128 v130, v[78:81] offset:10240
	ds_write_b128 v130, v[86:89] offset:30720
	ds_write_b128 v130, v[94:97] offset:15360
	ds_write_b128 v130, v[102:105] offset:35840
	s_waitcnt lgkmcnt(0)
	s_barrier
	v_mov_b32_e32 v131, v195
	v_and_b32_e32 v143, 15, v131
	v_or_b32_e32 v144, v143, v140
	v_and_b32_e32 v148, 48, v131
	v_mul_u32_u24_e32 v131, 0x50, v144
	v_lshl_add_u32 v131, v131, 1, v148
	v_or_b32_e32 v143, v143, v142
	v_mad_u32_u24 v238, v143, s36, v148
	ds_read_b128 v[144:147], v131 offset:20480
	ds_read_b128 v[160:163], v238
	ds_read_b128 v[164:167], v238 offset:2560
	ds_read_b128 v[168:171], v238 offset:5120
	ds_read_b128 v[172:175], v238 offset:7680
	ds_read_b128 v[148:151], v131 offset:23040
	ds_read_b128 v[152:155], v131 offset:25600
	ds_read_b128 v[156:159], v131 offset:28160
	ds_read_b128 v[176:179], v238 offset:64
	ds_read_b128 v[180:183], v238 offset:2624
	s_cbranch_vccnz .Lgw_skip_4
	v_add_co_u32_e32 v42, vcc, 0x19700000, v138
	s_nop 1
	v_addc_co_u32_e32 v43, vcc, 0, v139, vcc
	v_add_co_u32_e32 v50, vcc, 0xa6e0000, v136
	global_load_dwordx4 v[42:45], v[42:43], off offset:256
	s_nop 0
	v_addc_co_u32_e32 v51, vcc, 0, v137, vcc
	v_add_co_u32_e32 v62, vcc, 0x19711000, v138
	global_load_dwordx4 v[50:53], v[50:51], off offset:256
	s_nop 0
	v_addc_co_u32_e32 v63, vcc, 0, v139, vcc
	v_add_co_u32_e32 v70, vcc, 0xa6f1000, v136
	global_load_dwordx4 v[62:65], v[62:63], off offset:256
	s_nop 0
	v_addc_co_u32_e32 v71, vcc, 0, v137, vcc
	v_add_co_u32_e32 v78, vcc, 0x19722000, v138
	global_load_dwordx4 v[70:73], v[70:71], off offset:256
	s_nop 0
	v_addc_co_u32_e32 v79, vcc, 0, v139, vcc
	v_add_co_u32_e32 v86, vcc, 0xa702000, v136
	global_load_dwordx4 v[78:81], v[78:79], off offset:256
	s_nop 0
	v_addc_co_u32_e32 v87, vcc, 0, v137, vcc
	v_add_co_u32_e32 v94, vcc, 0x19733000, v138
	global_load_dwordx4 v[86:89], v[86:87], off offset:256
	s_nop 0
	v_addc_co_u32_e32 v95, vcc, 0, v139, vcc
	v_add_co_u32_e32 v102, vcc, 0xa713000, v136
	global_load_dwordx4 v[94:97], v[94:95], off offset:256
	s_nop 0
	v_addc_co_u32_e32 v103, vcc, 0, v137, vcc
	global_load_dwordx4 v[102:105], v[102:103], off offset:256
; DEV f32x4 mfma16(bf16x8 a, bf16x8 b, f32x4 c) { return __builtin_amdgcn_mfma_f32_16x16x32_bf16(a, b, c, 0, 0, 0); }
; #define G_LOAD(RA, RB, KT) { _Pragma("unroll") for (int i = 0; i < 4; i++) { \
;       RA[i] = *(const u32x4*)(Ap + (size_t)(i * 32) * lda + (KT) * 64); RB[i] = *(const u32x4*)(Bp + (size_t)(i * 32) * ldb + (KT) * 64); } }
; #define G_STORE(RA, RB) { _Pragma("unroll") for (int i = 0; i < 4; i++) { \
;       *(u32x4*)(As + (lrow + i * 32) * GLD + lcc * 8) = RA[i]; *(u32x4*)(Bs + (lrow + i * 32) * GLD + lcc * 8) = RB[i]; } }
; template <int TI, int TJ, int KS>
; DEV void mfma_lds(const bf16_t* Arows, int lda, const bf16_t* Brows, int ldb, int i0, int j0, f32x4 (&acc)[TI][TJ]) {
;     ...
;   for (int ks = 0; ks < KS; ks++) {
;     bf16x8 af[TI], bfr[TJ];
; #pragma unroll
;     for (int i = 0; i < TI; i++) af[i] = *(const bf16x8*)(Arows + (i0 + i * 16 + l15) * lda + ks * 32 + quad * 8);
; #pragma unroll
;     for (int j = 0; j < TJ; j++) bfr[j] = *(const bf16x8*)(Brows + (j0 + j * 16 + l15) * ldb + ks * 32 + quad * 8);
; #pragma unroll
;     for (int i = 0; i < TI; i++)
; #pragma unroll
;       for (int j = 0; j < TJ; j++) acc[i][j] = mfma16(af[i], bfr[j], acc[i][j]);
;   }
; template <class Epi>
; DEV void gemm_tile(const bf16_t* __restrict__ A, int lda, const bf16_t* __restrict__ Bt, int ldb, int K, int m0, int n0,
;                    Epi& epi, char* smem) {
;     ...
;   for (int kt = 0; kt < nk; kt += 2) {
;     __syncthreads();
;     G_STORE(ra0, rb0);
;     __syncthreads();
;     if (kt + 2 < nk) G_LOAD(ra0, rb0, kt + 2);
;     mfma_lds<4, 4, 2>(Bs, GLD, As, GLD, wn * 64, wm * 64, acc);
;     __syncthreads();
;     G_STORE(ra1, rb1);
;     __syncthreads();
;     if (kt + 3 < nk) G_LOAD(ra1, rb1, kt + 3);
;     mfma_lds<4, 4, 2>(Bs, GLD, As, GLD, wn * 64, wm * 64, acc);
;   }
.LBB0_673:
	s_cmp_gt_u32 s15, 12
	s_waitcnt lgkmcnt(8)
	v_mfma_f32_16x16x32_bf16 v[126:129], v[144:147], v[160:163], v[126:129]
	s_waitcnt lgkmcnt(7)
	v_mfma_f32_16x16x32_bf16 v[122:125], v[144:147], v[164:167], v[122:125]
	s_waitcnt lgkmcnt(6)
	v_mfma_f32_16x16x32_bf16 v[118:121], v[144:147], v[168:171], v[118:121]
	s_waitcnt lgkmcnt(5)
	v_mfma_f32_16x16x32_bf16 v[114:117], v[144:147], v[172:175], v[114:117]
	ds_read_b128 v[144:147], v131 offset:20544
	s_waitcnt lgkmcnt(5)
	v_mfma_f32_16x16x32_bf16 v[110:113], v[148:151], v[160:163], v[110:113]
	v_mfma_f32_16x16x32_bf16 v[58:61], v[148:151], v[164:167], v[58:61]
	v_mfma_f32_16x16x32_bf16 v[38:41], v[148:151], v[168:171], v[38:41]
	v_mfma_f32_16x16x32_bf16 v[34:37], v[148:151], v[172:175], v[34:37]
	ds_read_b128 v[148:151], v131 offset:23104
	s_waitcnt lgkmcnt(5)
	v_mfma_f32_16x16x32_bf16 v[30:33], v[152:155], v[160:163], v[30:33]
	v_mfma_f32_16x16x32_bf16 v[26:29], v[152:155], v[164:167], v[26:29]
	v_mfma_f32_16x16x32_bf16 v[22:25], v[152:155], v[168:171], v[22:25]
	v_mfma_f32_16x16x32_bf16 v[18:21], v[152:155], v[172:175], v[18:21]
	ds_read_b128 v[152:155], v131 offset:25664
	s_waitcnt lgkmcnt(5)
	v_mfma_f32_16x16x32_bf16 v[6:9], v[156:159], v[168:171], v[6:9]
	v_mfma_f32_16x16x32_bf16 v[2:5], v[156:159], v[172:175], v[2:5]
	ds_read_b128 v[168:171], v238 offset:5184
	ds_read_b128 v[172:175], v238 offset:7744
	v_mfma_f32_16x16x32_bf16 v[14:17], v[156:159], v[160:163], v[14:17]
	v_mfma_f32_16x16x32_bf16 v[10:13], v[156:159], v[164:167], v[10:13]
	ds_read_b128 v[156:159], v131 offset:28224
	s_waitcnt lgkmcnt(5)
	v_mfma_f32_16x16x32_bf16 v[126:129], v[144:147], v[176:179], v[126:129]
	s_waitcnt lgkmcnt(4)
	v_mfma_f32_16x16x32_bf16 v[110:113], v[148:151], v[176:179], v[110:113]
	s_waitcnt lgkmcnt(3)
	v_mfma_f32_16x16x32_bf16 v[30:33], v[152:155], v[176:179], v[30:33]
	v_mfma_f32_16x16x32_bf16 v[122:125], v[144:147], v[180:183], v[122:125]
	v_mfma_f32_16x16x32_bf16 v[58:61], v[148:151], v[180:183], v[58:61]
	v_mfma_f32_16x16x32_bf16 v[26:29], v[152:155], v[180:183], v[26:29]
	s_waitcnt lgkmcnt(2)
	v_mfma_f32_16x16x32_bf16 v[118:121], v[144:147], v[168:171], v[118:121]
	v_mfma_f32_16x16x32_bf16 v[38:41], v[148:151], v[168:171], v[38:41]
	v_mfma_f32_16x16x32_bf16 v[22:25], v[152:155], v[168:171], v[22:25]
	s_waitcnt lgkmcnt(1)
	v_mfma_f32_16x16x32_bf16 v[114:117], v[144:147], v[172:175], v[114:117]
	v_mfma_f32_16x16x32_bf16 v[34:37], v[148:151], v[172:175], v[34:37]
	v_mfma_f32_16x16x32_bf16 v[18:21], v[152:155], v[172:175], v[18:21]
	s_waitcnt lgkmcnt(0)
	v_mfma_f32_16x16x32_bf16 v[14:17], v[156:159], v[176:179], v[14:17]
	s_barrier
	v_mfma_f32_16x16x32_bf16 v[10:13], v[156:159], v[180:183], v[10:13]
	s_waitcnt vmcnt(8)
	ds_write_b128 v130, v[46:49]
	ds_write_b128 v130, v[54:57] offset:20480
	ds_write_b128 v130, v[66:69] offset:5120
	ds_write_b128 v130, v[74:77] offset:25600
	ds_write_b128 v130, v[82:85] offset:10240
	ds_write_b128 v130, v[90:93] offset:30720
	ds_write_b128 v130, v[98:101] offset:15360
	ds_write_b128 v130, v[106:109] offset:35840
	v_mfma_f32_16x16x32_bf16 v[6:9], v[156:159], v[168:171], v[6:9]
	v_mfma_f32_16x16x32_bf16 v[2:5], v[156:159], v[172:175], v[2:5]
	s_waitcnt lgkmcnt(0)
	s_barrier
	ds_read_b128 v[144:147], v131 offset:20480
	ds_read_b128 v[160:163], v238
	ds_read_b128 v[164:167], v238 offset:2560
	ds_read_b128 v[168:171], v238 offset:5120
	ds_read_b128 v[172:175], v238 offset:7680
	ds_read_b128 v[148:151], v131 offset:23040
	ds_read_b128 v[152:155], v131 offset:25600
	ds_read_b128 v[156:159], v131 offset:28160
	ds_read_b128 v[176:179], v238 offset:64
	ds_read_b128 v[180:183], v238 offset:2624
	s_cbranch_scc1 .LBB0_670
	v_add_co_u32_e32 v46, vcc, 0x19700000, v138
	s_nop 1
	v_addc_co_u32_e32 v47, vcc, 0, v139, vcc
	v_add_co_u32_e32 v54, vcc, 0xa6e0000, v136
	global_load_dwordx4 v[46:49], v[46:47], off offset:384
	s_nop 0
	v_addc_co_u32_e32 v55, vcc, 0, v137, vcc
	v_add_co_u32_e32 v66, vcc, 0x19711000, v138
	global_load_dwordx4 v[54:57], v[54:55], off offset:384
	s_nop 0
	v_addc_co_u32_e32 v67, vcc, 0, v139, vcc
	v_add_co_u32_e32 v74, vcc, 0xa6f1000, v136
	global_load_dwordx4 v[66:69], v[66:67], off offset:384
	s_nop 0
	v_addc_co_u32_e32 v75, vcc, 0, v137, vcc
	v_add_co_u32_e32 v82, vcc, 0x19722000, v138
	global_load_dwordx4 v[74:77], v[74:75], off offset:384
	s_nop 0
	v_addc_co_u32_e32 v83, vcc, 0, v139, vcc
	v_add_co_u32_e32 v90, vcc, 0xa702000, v136
	global_load_dwordx4 v[82:85], v[82:83], off offset:384
	s_nop 0
	v_addc_co_u32_e32 v91, vcc, 0, v137, vcc
	v_add_co_u32_e32 v98, vcc, 0x19733000, v138
	global_load_dwordx4 v[90:93], v[90:91], off offset:384
	s_nop 0
	v_addc_co_u32_e32 v99, vcc, 0, v139, vcc
	v_add_co_u32_e32 v106, vcc, 0xa713000, v136
	global_load_dwordx4 v[98:101], v[98:99], off offset:384
	s_nop 0
	v_addc_co_u32_e32 v107, vcc, 0, v137, vcc
	global_load_dwordx4 v[106:109], v[106:107], off offset:384
	s_branch .LBB0_670

; DEV f32x4 mfma16(bf16x8 a, bf16x8 b, f32x4 c) { return __builtin_amdgcn_mfma_f32_16x16x32_bf16(a, b, c, 0, 0, 0); }
; #define G_LOAD(RA, RB, KT) { _Pragma("unroll") for (int i = 0; i < 4; i++) { \
;       RA[i] = *(const u32x4*)(Ap + (size_t)(i * 32) * lda + (KT) * 64); RB[i] = *(const u32x4*)(Bp + (size_t)(i * 32) * ldb + (KT) * 64); } }
; #define G_STORE(RA, RB) { _Pragma("unroll") for (int i = 0; i < 4; i++) { \
;       *(u32x4*)(As + (lrow + i * 32) * GLD + lcc * 8) = RA[i]; *(u32x4*)(Bs + (lrow + i * 32) * GLD + lcc * 8) = RB[i]; } }
; template <int TI, int TJ, int KS>
; DEV void mfma_lds(const bf16_t* Arows, int lda, const bf16_t* Brows, int ldb, int i0, int j0, f32x4 (&acc)[TI][TJ]) {
;     ...
;   for (int ks = 0; ks < KS; ks++) {
;     bf16x8 af[TI], bfr[TJ];
; #pragma unroll
;     for (int i = 0; i < TI; i++) af[i] = *(const bf16x8*)(Arows + (i0 + i * 16 + l15) * lda + ks * 32 + quad * 8);
; #pragma unroll
;     for (int j = 0; j < TJ; j++) bfr[j] = *(const bf16x8*)(Brows + (j0 + j * 16 + l15) * ldb + ks * 32 + quad * 8);
; #pragma unroll
;     for (int i = 0; i < TI; i++)
; #pragma unroll
;       for (int j = 0; j < TJ; j++) acc[i][j] = mfma16(af[i], bfr[j], acc[i][j]);
;   }
; template <class Epi>
; DEV void gemm_tile(const bf16_t* __restrict__ A, int lda, const bf16_t* __restrict__ Bt, int ldb, int K, int m0, int n0,
;                    Epi& epi, char* smem) {
;     ...
;   for (int kt = 0; kt < nk; kt += 2) {
;     __syncthreads();
;     G_STORE(ra0, rb0);
;     __syncthreads();
;     if (kt + 2 < nk) G_LOAD(ra0, rb0, kt + 2);
;     mfma_lds<4, 4, 2>(Bs, GLD, As, GLD, wn * 64, wm * 64, acc);
;     __syncthreads();
;     G_STORE(ra1, rb1);
;     __syncthreads();
;     if (kt + 3 < nk) G_LOAD(ra1, rb1, kt + 3);
;     mfma_lds<4, 4, 2>(Bs, GLD, As, GLD, wn * 64, wm * 64, acc);
;   }
.LBB0_1038:
	v_lshl_add_u64 v[132:133], v[132:133], 0, s[34:35]
	v_lshl_add_u64 v[134:135], v[134:135], 0, s[34:35]
	s_and_b64 vcc, exec, s[8:9]
	s_waitcnt lgkmcnt(8)
	v_mfma_f32_16x16x32_bf16 v[114:117], v[148:151], v[164:167], v[114:117]
	s_waitcnt lgkmcnt(7)
	v_mfma_f32_16x16x32_bf16 v[126:129], v[148:151], v[168:171], v[126:129]
	s_waitcnt lgkmcnt(6)
	v_mfma_f32_16x16x32_bf16 v[122:125], v[148:151], v[172:175], v[122:125]
	s_waitcnt lgkmcnt(5)
	v_mfma_f32_16x16x32_bf16 v[118:121], v[148:151], v[176:179], v[118:121]
	ds_read_b128 v[148:151], v131 offset:20544
	s_waitcnt lgkmcnt(5)
	v_mfma_f32_16x16x32_bf16 v[110:113], v[152:155], v[164:167], v[110:113]
	v_mfma_f32_16x16x32_bf16 v[106:109], v[152:155], v[168:171], v[106:109]
	v_mfma_f32_16x16x32_bf16 v[102:105], v[152:155], v[172:175], v[102:105]
	v_mfma_f32_16x16x32_bf16 v[98:101], v[152:155], v[176:179], v[98:101]
	ds_read_b128 v[152:155], v131 offset:23104
	s_waitcnt lgkmcnt(5)
	v_mfma_f32_16x16x32_bf16 v[94:97], v[156:159], v[164:167], v[94:97]
	v_mfma_f32_16x16x32_bf16 v[82:85], v[156:159], v[168:171], v[82:85]
	v_mfma_f32_16x16x32_bf16 v[78:81], v[156:159], v[172:175], v[78:81]
	v_mfma_f32_16x16x32_bf16 v[70:73], v[156:159], v[176:179], v[70:73]
	ds_read_b128 v[156:159], v131 offset:25664
	s_waitcnt lgkmcnt(5)
	v_mfma_f32_16x16x32_bf16 v[66:69], v[160:163], v[172:175], v[66:69]
	v_mfma_f32_16x16x32_bf16 v[90:93], v[160:163], v[176:179], v[90:93]
	ds_read_b128 v[172:175], v238 offset:5184
	ds_read_b128 v[176:179], v238 offset:7744
	v_mfma_f32_16x16x32_bf16 v[86:89], v[160:163], v[164:167], v[86:89]
	v_mfma_f32_16x16x32_bf16 v[74:77], v[160:163], v[168:171], v[74:77]
	ds_read_b128 v[160:163], v131 offset:28224
	s_waitcnt lgkmcnt(5)
	v_mfma_f32_16x16x32_bf16 v[114:117], v[148:151], v[180:183], v[114:117]
	s_waitcnt lgkmcnt(4)
	v_mfma_f32_16x16x32_bf16 v[110:113], v[152:155], v[180:183], v[110:113]
	s_waitcnt lgkmcnt(3)
	v_mfma_f32_16x16x32_bf16 v[94:97], v[156:159], v[180:183], v[94:97]
	v_mfma_f32_16x16x32_bf16 v[126:129], v[148:151], v[184:187], v[126:129]
	v_mfma_f32_16x16x32_bf16 v[106:109], v[152:155], v[184:187], v[106:109]
	v_mfma_f32_16x16x32_bf16 v[82:85], v[156:159], v[184:187], v[82:85]
	s_waitcnt lgkmcnt(2)
	v_mfma_f32_16x16x32_bf16 v[122:125], v[148:151], v[172:175], v[122:125]
	v_mfma_f32_16x16x32_bf16 v[102:105], v[152:155], v[172:175], v[102:105]
	v_mfma_f32_16x16x32_bf16 v[78:81], v[156:159], v[172:175], v[78:81]
	s_waitcnt lgkmcnt(1)
	v_mfma_f32_16x16x32_bf16 v[118:121], v[148:151], v[176:179], v[118:121]
	v_mfma_f32_16x16x32_bf16 v[98:101], v[152:155], v[176:179], v[98:101]
	v_mfma_f32_16x16x32_bf16 v[70:73], v[156:159], v[176:179], v[70:73]
	s_waitcnt lgkmcnt(0)
	v_mfma_f32_16x16x32_bf16 v[86:89], v[160:163], v[180:183], v[86:89]
	v_mfma_f32_16x16x32_bf16 v[74:77], v[160:163], v[184:187], v[74:77]
	v_mfma_f32_16x16x32_bf16 v[66:69], v[160:163], v[172:175], v[66:69]
	v_mfma_f32_16x16x32_bf16 v[90:93], v[160:163], v[176:179], v[90:93]
	s_cbranch_vccnz .LBB0_1043
.LBB0_1039:
	s_add_i32 s14, s14, 2
	s_cmp_gt_u32 s14, 13
	s_cselect_b64 s[8:9], -1, 0
	s_and_b64 vcc, exec, s[8:9]
	v_lshl_add_u64 v[138:139], v[134:135], 0, v[0:1]
	v_lshl_add_u64 v[136:137], v[132:133], 0, v[0:1]
	s_waitcnt lgkmcnt(0)
	s_barrier
	s_waitcnt vmcnt(8)
	ds_write_b128 v130, v[2:5]
	ds_write_b128 v130, v[10:13] offset:20480
	ds_write_b128 v130, v[18:21] offset:5120
	ds_write_b128 v130, v[26:29] offset:25600
	ds_write_b128 v130, v[34:37] offset:10240
	ds_write_b128 v130, v[42:45] offset:30720
	ds_write_b128 v130, v[50:53] offset:15360
	ds_write_b128 v130, v[58:61] offset:35840
	s_waitcnt lgkmcnt(0)
	s_barrier
	v_mov_b32_e32 v131, v195
	v_and_b32_e32 v143, 15, v131
	v_or_b32_e32 v144, v143, v141
	v_and_b32_e32 v148, 48, v131
	v_mul_u32_u24_e32 v131, 0x50, v144
	v_lshl_add_u32 v131, v131, 1, v148
	v_or_b32_e32 v143, v143, v142
	v_mad_u32_u24 v238, v143, s36, v148
	ds_read_b128 v[148:151], v131 offset:20480
	ds_read_b128 v[164:167], v238
	ds_read_b128 v[168:171], v238 offset:2560
	ds_read_b128 v[172:175], v238 offset:5120
	ds_read_b128 v[176:179], v238 offset:7680
	ds_read_b128 v[152:155], v131 offset:23040
	ds_read_b128 v[156:159], v131 offset:25600
	ds_read_b128 v[160:163], v131 offset:28160
	ds_read_b128 v[180:183], v238 offset:64
	ds_read_b128 v[184:187], v238 offset:2624
	s_cbranch_vccnz .Lgw_skip_5
	v_add_co_u32_e32 v2, vcc, 0x4200000, v138
	s_nop 1
	v_addc_co_u32_e32 v3, vcc, 0, v139, vcc
	v_add_co_u32_e32 v10, vcc, 0xa300000, v136
	global_load_dwordx4 v[2:5], v[2:3], off offset:256
	s_nop 0
	v_addc_co_u32_e32 v11, vcc, 0, v137, vcc
	v_add_co_u32_e32 v18, vcc, 0x4211000, v138
	global_load_dwordx4 v[10:13], v[10:11], off offset:256
	s_nop 0
	v_addc_co_u32_e32 v19, vcc, 0, v139, vcc
	v_add_co_u32_e32 v26, vcc, 0xa311000, v136
	global_load_dwordx4 v[18:21], v[18:19], off offset:256
	s_nop 0
	v_addc_co_u32_e32 v27, vcc, 0, v137, vcc
	v_add_co_u32_e32 v34, vcc, 0x4222000, v138
	global_load_dwordx4 v[26:29], v[26:27], off offset:256
	s_nop 0
	v_addc_co_u32_e32 v35, vcc, 0, v139, vcc
	v_add_co_u32_e32 v42, vcc, 0xa322000, v136
	global_load_dwordx4 v[34:37], v[34:35], off offset:256
	s_nop 0
	v_addc_co_u32_e32 v43, vcc, 0, v137, vcc
	v_add_co_u32_e32 v50, vcc, 0x4233000, v138
	global_load_dwordx4 v[42:45], v[42:43], off offset:256
	s_nop 0
	v_addc_co_u32_e32 v51, vcc, 0, v139, vcc
	v_add_co_u32_e32 v58, vcc, 0xa333000, v136
	global_load_dwordx4 v[50:53], v[50:51], off offset:256
	s_nop 0
	v_addc_co_u32_e32 v59, vcc, 0, v137, vcc
	global_load_dwordx4 v[58:61], v[58:59], off offset:256
; DEV f32x4 mfma16(bf16x8 a, bf16x8 b, f32x4 c) { return __builtin_amdgcn_mfma_f32_16x16x32_bf16(a, b, c, 0, 0, 0); }
; #define G_LOAD(RA, RB, KT) { _Pragma("unroll") for (int i = 0; i < 4; i++) { \
;       RA[i] = *(const u32x4*)(Ap + (size_t)(i * 32) * lda + (KT) * 64); RB[i] = *(const u32x4*)(Bp + (size_t)(i * 32) * ldb + (KT) * 64); } }
; #define G_STORE(RA, RB) { _Pragma("unroll") for (int i = 0; i < 4; i++) { \
;       *(u32x4*)(As + (lrow + i * 32) * GLD + lcc * 8) = RA[i]; *(u32x4*)(Bs + (lrow + i * 32) * GLD + lcc * 8) = RB[i]; } }
; template <int TI, int TJ, int KS>
; DEV void mfma_lds(const bf16_t* Arows, int lda, const bf16_t* Brows, int ldb, int i0, int j0, f32x4 (&acc)[TI][TJ]) {
;     ...
;   for (int ks = 0; ks < KS; ks++) {
;     bf16x8 af[TI], bfr[TJ];
; #pragma unroll
;     for (int i = 0; i < TI; i++) af[i] = *(const bf16x8*)(Arows + (i0 + i * 16 + l15) * lda + ks * 32 + quad * 8);
; #pragma unroll
;     for (int j = 0; j < TJ; j++) bfr[j] = *(const bf16x8*)(Brows + (j0 + j * 16 + l15) * ldb + ks * 32 + quad * 8);
; #pragma unroll
;     for (int i = 0; i < TI; i++)
; #pragma unroll
;       for (int j = 0; j < TJ; j++) acc[i][j] = mfma16(af[i], bfr[j], acc[i][j]);
;   }
; template <class Epi>
; DEV void gemm_tile(const bf16_t* __restrict__ A, int lda, const bf16_t* __restrict__ Bt, int ldb, int K, int m0, int n0,
;                    Epi& epi, char* smem) {
;     ...
;   for (int kt = 0; kt < nk; kt += 2) {
;     __syncthreads();
;     G_STORE(ra0, rb0);
;     __syncthreads();
;     if (kt + 2 < nk) G_LOAD(ra0, rb0, kt + 2);
;     mfma_lds<4, 4, 2>(Bs, GLD, As, GLD, wn * 64, wm * 64, acc);
;     __syncthreads();
;     G_STORE(ra1, rb1);
;     __syncthreads();
;     if (kt + 3 < nk) G_LOAD(ra1, rb1, kt + 3);
;     mfma_lds<4, 4, 2>(Bs, GLD, As, GLD, wn * 64, wm * 64, acc);
;   }
.LBB0_1041:
	s_cmp_gt_u32 s14, 12
	s_waitcnt lgkmcnt(8)
	v_mfma_f32_16x16x32_bf16 v[114:117], v[148:151], v[164:167], v[114:117]
	s_waitcnt lgkmcnt(7)
	v_mfma_f32_16x16x32_bf16 v[126:129], v[148:151], v[168:171], v[126:129]
	s_waitcnt lgkmcnt(6)
	v_mfma_f32_16x16x32_bf16 v[122:125], v[148:151], v[172:175], v[122:125]
	s_waitcnt lgkmcnt(5)
	v_mfma_f32_16x16x32_bf16 v[118:121], v[148:151], v[176:179], v[118:121]
	ds_read_b128 v[148:151], v131 offset:20544
	s_waitcnt lgkmcnt(5)
	v_mfma_f32_16x16x32_bf16 v[110:113], v[152:155], v[164:167], v[110:113]
	v_mfma_f32_16x16x32_bf16 v[106:109], v[152:155], v[168:171], v[106:109]
	v_mfma_f32_16x16x32_bf16 v[102:105], v[152:155], v[172:175], v[102:105]
	v_mfma_f32_16x16x32_bf16 v[98:101], v[152:155], v[176:179], v[98:101]
	ds_read_b128 v[152:155], v131 offset:23104
	s_waitcnt lgkmcnt(5)
	v_mfma_f32_16x16x32_bf16 v[94:97], v[156:159], v[164:167], v[94:97]
	v_mfma_f32_16x16x32_bf16 v[82:85], v[156:159], v[168:171], v[82:85]
	v_mfma_f32_16x16x32_bf16 v[78:81], v[156:159], v[172:175], v[78:81]
	v_mfma_f32_16x16x32_bf16 v[70:73], v[156:159], v[176:179], v[70:73]
	ds_read_b128 v[156:159], v131 offset:25664
	s_waitcnt lgkmcnt(5)
	v_mfma_f32_16x16x32_bf16 v[66:69], v[160:163], v[172:175], v[66:69]
	v_mfma_f32_16x16x32_bf16 v[90:93], v[160:163], v[176:179], v[90:93]
	ds_read_b128 v[172:175], v238 offset:5184
	ds_read_b128 v[176:179], v238 offset:7744
	v_mfma_f32_16x16x32_bf16 v[86:89], v[160:163], v[164:167], v[86:89]
	v_mfma_f32_16x16x32_bf16 v[74:77], v[160:163], v[168:171], v[74:77]
	ds_read_b128 v[160:163], v131 offset:28224
	s_waitcnt lgkmcnt(5)
	v_mfma_f32_16x16x32_bf16 v[114:117], v[148:151], v[180:183], v[114:117]
	s_waitcnt lgkmcnt(4)
	v_mfma_f32_16x16x32_bf16 v[110:113], v[152:155], v[180:183], v[110:113]
	s_waitcnt lgkmcnt(3)
	v_mfma_f32_16x16x32_bf16 v[94:97], v[156:159], v[180:183], v[94:97]
	v_mfma_f32_16x16x32_bf16 v[126:129], v[148:151], v[184:187], v[126:129]
	v_mfma_f32_16x16x32_bf16 v[106:109], v[152:155], v[184:187], v[106:109]
	v_mfma_f32_16x16x32_bf16 v[82:85], v[156:159], v[184:187], v[82:85]
	s_waitcnt lgkmcnt(2)
	v_mfma_f32_16x16x32_bf16 v[122:125], v[148:151], v[172:175], v[122:125]
	v_mfma_f32_16x16x32_bf16 v[102:105], v[152:155], v[172:175], v[102:105]
	v_mfma_f32_16x16x32_bf16 v[78:81], v[156:159], v[172:175], v[78:81]
	s_waitcnt lgkmcnt(1)
	v_mfma_f32_16x16x32_bf16 v[118:121], v[148:151], v[176:179], v[118:121]
	v_mfma_f32_16x16x32_bf16 v[98:101], v[152:155], v[176:179], v[98:101]
	v_mfma_f32_16x16x32_bf16 v[70:73], v[156:159], v[176:179], v[70:73]
	s_waitcnt lgkmcnt(0)
	v_mfma_f32_16x16x32_bf16 v[86:89], v[160:163], v[180:183], v[86:89]
	s_barrier
	v_mfma_f32_16x16x32_bf16 v[74:77], v[160:163], v[184:187], v[74:77]
	s_waitcnt vmcnt(8)
	ds_write_b128 v130, v[6:9]
	ds_write_b128 v130, v[14:17] offset:20480
	ds_write_b128 v130, v[22:25] offset:5120
	ds_write_b128 v130, v[30:33] offset:25600
	ds_write_b128 v130, v[38:41] offset:10240
	ds_write_b128 v130, v[46:49] offset:30720
	ds_write_b128 v130, v[54:57] offset:15360
	ds_write_b128 v130, v[62:65] offset:35840
	v_mfma_f32_16x16x32_bf16 v[66:69], v[160:163], v[172:175], v[66:69]
	v_mfma_f32_16x16x32_bf16 v[90:93], v[160:163], v[176:179], v[90:93]
	s_waitcnt lgkmcnt(0)
	s_barrier
	ds_read_b128 v[148:151], v131 offset:20480
	ds_read_b128 v[164:167], v238
	ds_read_b128 v[168:171], v238 offset:2560
	ds_read_b128 v[172:175], v238 offset:5120
	ds_read_b128 v[176:179], v238 offset:7680
	ds_read_b128 v[152:155], v131 offset:23040
	ds_read_b128 v[156:159], v131 offset:25600
	ds_read_b128 v[160:163], v131 offset:28160
	ds_read_b128 v[180:183], v238 offset:64
	ds_read_b128 v[184:187], v238 offset:2624
	s_cbranch_scc1 .LBB0_1038
	v_add_co_u32_e32 v6, vcc, 0x4200000, v138
	s_nop 1
	v_addc_co_u32_e32 v7, vcc, 0, v139, vcc
	v_add_co_u32_e32 v14, vcc, 0xa300000, v136
	global_load_dwordx4 v[6:9], v[6:7], off offset:384
	s_nop 0
	v_addc_co_u32_e32 v15, vcc, 0, v137, vcc
	v_add_co_u32_e32 v22, vcc, 0x4211000, v138
	global_load_dwordx4 v[14:17], v[14:15], off offset:384
	s_nop 0
	v_addc_co_u32_e32 v23, vcc, 0, v139, vcc
	v_add_co_u32_e32 v30, vcc, 0xa311000, v136
	global_load_dwordx4 v[22:25], v[22:23], off offset:384
	s_nop 0
	v_addc_co_u32_e32 v31, vcc, 0, v137, vcc
	v_add_co_u32_e32 v38, vcc, 0x4222000, v138
	global_load_dwordx4 v[30:33], v[30:31], off offset:384
	s_nop 0
	v_addc_co_u32_e32 v39, vcc, 0, v139, vcc
	v_add_co_u32_e32 v46, vcc, 0xa322000, v136
	global_load_dwordx4 v[38:41], v[38:39], off offset:384
	s_nop 0
	v_addc_co_u32_e32 v47, vcc, 0, v137, vcc
	v_add_co_u32_e32 v54, vcc, 0x4233000, v138
	global_load_dwordx4 v[46:49], v[46:47], off offset:384
	s_nop 0
	v_addc_co_u32_e32 v55, vcc, 0, v139, vcc
	v_add_co_u32_e32 v62, vcc, 0xa333000, v136
	global_load_dwordx4 v[54:57], v[54:55], off offset:384
	s_nop 0
	v_addc_co_u32_e32 v63, vcc, 0, v137, vcc
	global_load_dwordx4 v[62:65], v[62:63], off offset:384
	s_branch .LBB0_1038
